# tile-final barriers removed where the tile's last LDS reads are already fenced (ml_out) or the tile uses no LDS (hy_merge, hy_prep)
# baseline (speedup 1.0000x reference)
; __device__ __forceinline__ float bf2f(bf16_t h) { return __uint_as_float(((unsigned)h) << 16); }
; __device__ void hy_prep_tile(unsigned char* lds, const Params& p, int l, int b, int ck) {
;     ...
;   const bool isctx = ck < 4;
;   const int L = isctx ? 256 : 2048;
;   const int t0 = isctx ? ck * 64 : (ck - 4) * 64;
;   const int rowbase = isctx ? (NLAT + b * 256) : (b * 2048);
;   const int posoff = isctx ? 2048 : 0;
;   {
;     const int c = tid & 255, half = tid >> 8;
;     const float* wc = p.in[9] + (size_t)l * 3 * 768;
;     const float a0 = wc[256 + c], a1 = wc[768 + 256 + c], a2 = wc[1536 + 256 + c];
;     const float v0 = wc[512 + c], v1 = wc[768 + 512 + c], v2 = wc[1536 + 512 + c];
;     const int ts = t0 + half * 32;
;     float xp, xc, xn, vp, vc, vn;
;     { const int tq = ts - 1 >= 0 ? ts - 1 : 0; const float mk = ts - 1 >= 0 ? 1.f : 0.f;
;       xp = mk * bf2f(z[(size_t)(rowbase + tq) * ZS + 256 + c]); vp = mk * bf2f(z[(size_t)(rowbase + tq) * ZS + 512 + c]); }
;     xc = bf2f(z[(size_t)(rowbase + ts) * ZS + 256 + c]); vc = bf2f(z[(size_t)(rowbase + ts) * ZS + 512 + c]);
; #pragma unroll 8
;     for (int q = 0; q < 32; ++q) {
;       const int tp = ts + q;
;       { const int tq = tp + 1 < L ? tp + 1 : L - 1; const float mk = tp + 1 < L ? 1.f : 0.f;
;         xn = mk * bf2f(z[(size_t)(rowbase + tq) * ZS + 256 + c]); vn = mk * bf2f(z[(size_t)(rowbase + tq) * ZS + 512 + c]); }
; __global__ void __launch_bounds__(512) fwd_kernel(Params p) {
;     ...
;     for (int item = blockIdx.x; item < 576 + 1152 + 288; item += G_) {
;       if (item < 576) {
;         const int n = item % 18, bh = item / 18;
;         ml_local_tile(lds, p, l, bh >> 2, bh & 3, n);
;       } else if (item < 576 + 1152) {
;         const int tile = item - 576;
;         const int hh = tile & 3, ck = (tile >> 2) % 36, b = tile / 144;
;         rg_tile(lds, p, l, b, ck, hh, false);
;       } else {
;         const int tile = item - 576 - 1152;
;         hy_prep_tile(lds, p, l, tile / 36, tile % 36);
;       }
.LBB0_323:
	s_cmpk_gt_i32 s20, 0x23f
	s_mov_b64 s[0:1], -1
	s_cbranch_scc0 .LBB0_331
	s_cmpk_gt_u32 s20, 0x6bf
	s_cbranch_scc0 .LBB0_326
	s_add_i32 s0, s20, 0xf940
	s_and_b32 s1, s0, 0xffff
	s_mul_i32 s1, s1, 0xe38f
	s_lshr_b32 s1, s1, 21
	s_mul_i32 s2, s1, 36
	s_sub_i32 s0, s0, s2
	s_and_b32 s2, s0, 0xffff
	s_cmp_lt_u32 s2, 4
	s_cselect_b64 s[2:3], -1, 0
	s_and_b32 s0, s0, 0xffff
	s_lshl_b32 s4, s0, 6
	s_add_i32 s5, s4, 0xffffff00
	s_lshl_b32 s6, s1, 8
	s_add_i32 s6, s6, 0x4000
	s_lshl_b32 s7, s1, 11
	s_movk_i32 s8, 0x100
	s_movk_i32 s9, 0x800
	s_cmp_lt_u32 s0, 4
	s_cselect_b32 s44, s4, s5
	s_cselect_b32 s45, s8, s9
	s_cselect_b32 s46, s6, s7
	s_cselect_b32 s47, s9, 0
	v_readfirstlane_b32 s48, v195
	v_and_b32_e32 v50, 0xff, v195
	v_readlane_b32 s58, v251, 31
	v_readlane_b32 s59, v251, 32
	s_lshr_b32 s48, s48, 8
	s_lshl_b32 s49, s48, 5
	s_add_i32 s49, s49, s44
	s_mul_i32 s4, s1, 0x1200
	s_add_i32 s5, s47, s49
	s_lshl_b32 s5, s5, 1
	s_add_i32 s4, s4, s5
	s_add_u32 s58, s58, s4
	s_addc_u32 s59, s59, 0
	s_add_i32 s4, s46, s49
	s_mul_i32 s50, s4, 0x1a00
	s_add_i32 s4, s49, -1
	s_max_i32 s4, s4, 0
	s_add_i32 s4, s4, s46
	s_mul_i32 s51, s4, 0x1a00
	s_add_i32 s4, s49, 32
	s_add_i32 s5, s45, -1
	s_min_i32 s4, s4, s5
	s_add_i32 s4, s4, s46
	s_mul_i32 s5, s4, 0x1a00
	v_lshlrev_b32_e32 v55, 1, v50
	v_lshlrev_b32_e32 v53, 2, v50
	s_mov_b32 s6, 0x9000
	v_mul_lo_u32 v54, v50, s6
	v_add_u32_e32 v51, s50, v55
	v_add_u32_e32 v52, s51, v55
	v_add_u32_e32 v56, 0xc00, v53
	v_add_u32_e32 v57, 0x1800, v53
	global_load_dword v199, v53, s[14:15] offset:1024
	global_load_dword v202, v53, s[14:15] offset:2048
	global_load_dword v200, v56, s[14:15] offset:1024
	global_load_dword v203, v56, s[14:15] offset:2048
	global_load_dword v201, v57, s[14:15] offset:1024
	global_load_dword v204, v57, s[14:15] offset:2048
	global_load_ushort v0, v52, s[88:89] offset:512
	global_load_ushort v154, v52, s[88:89] offset:1024
	global_load_ushort v1, v51, s[88:89] offset:512
	global_load_ushort v155, v51, s[88:89] offset:1024
	v_add_u32_e32 v51, 0x1a00, v51
	global_load_ushort v2, v51, s[88:89] offset:512
	global_load_ushort v156, v51, s[88:89] offset:1024
	v_add_u32_e32 v51, 0x1a00, v51
	global_load_ushort v3, v51, s[88:89] offset:512
	global_load_ushort v157, v51, s[88:89] offset:1024
	v_add_u32_e32 v51, 0x1a00, v51
	global_load_ushort v4, v51, s[88:89] offset:512
	global_load_ushort v158, v51, s[88:89] offset:1024
	v_add_u32_e32 v51, 0x1a00, v51
	global_load_ushort v5, v51, s[88:89] offset:512
	global_load_ushort v159, v51, s[88:89] offset:1024
	v_add_u32_e32 v51, 0x1a00, v51
	global_load_ushort v6, v51, s[88:89] offset:512
	global_load_ushort v160, v51, s[88:89] offset:1024
	v_add_u32_e32 v51, 0x1a00, v51
	global_load_ushort v7, v51, s[88:89] offset:512
	global_load_ushort v161, v51, s[88:89] offset:1024
	v_add_u32_e32 v51, 0x1a00, v51
	global_load_ushort v8, v51, s[88:89] offset:512
	global_load_ushort v162, v51, s[88:89] offset:1024
	v_add_u32_e32 v51, 0x1a00, v51
	global_load_ushort v9, v51, s[88:89] offset:512
	global_load_ushort v163, v51, s[88:89] offset:1024
	v_add_u32_e32 v51, 0x1a00, v51
	global_load_ushort v10, v51, s[88:89] offset:512
	global_load_ushort v164, v51, s[88:89] offset:1024
	v_add_u32_e32 v51, 0x1a00, v51
	global_load_ushort v11, v51, s[88:89] offset:512
	global_load_ushort v165, v51, s[88:89] offset:1024
	v_add_u32_e32 v51, 0x1a00, v51
	global_load_ushort v12, v51, s[88:89] offset:512
	global_load_ushort v166, v51, s[88:89] offset:1024
	v_add_u32_e32 v51, 0x1a00, v51
	global_load_ushort v13, v51, s[88:89] offset:512
	global_load_ushort v167, v51, s[88:89] offset:1024
	v_add_u32_e32 v51, 0x1a00, v51
	global_load_ushort v14, v51, s[88:89] offset:512
	global_load_ushort v168, v51, s[88:89] offset:1024
	v_add_u32_e32 v51, 0x1a00, v51
	global_load_ushort v15, v51, s[88:89] offset:512
	global_load_ushort v169, v51, s[88:89] offset:1024
	v_add_u32_e32 v51, 0x1a00, v51
	global_load_ushort v16, v51, s[88:89] offset:512
	global_load_ushort v170, v51, s[88:89] offset:1024
	v_add_u32_e32 v51, 0x1a00, v51
	global_load_ushort v17, v51, s[88:89] offset:512
	global_load_ushort v171, v51, s[88:89] offset:1024
	v_add_u32_e32 v51, 0x1a00, v51
	global_load_ushort v18, v51, s[88:89] offset:512
	global_load_ushort v172, v51, s[88:89] offset:1024
	v_add_u32_e32 v51, 0x1a00, v51
	global_load_ushort v19, v51, s[88:89] offset:512
	global_load_ushort v173, v51, s[88:89] offset:1024
	v_add_u32_e32 v51, 0x1a00, v51
	global_load_ushort v20, v51, s[88:89] offset:512
	global_load_ushort v174, v51, s[88:89] offset:1024
	v_add_u32_e32 v51, 0x1a00, v51
	global_load_ushort v21, v51, s[88:89] offset:512
	global_load_ushort v175, v51, s[88:89] offset:1024
	v_add_u32_e32 v51, 0x1a00, v51
	global_load_ushort v22, v51, s[88:89] offset:512
	global_load_ushort v176, v51, s[88:89] offset:1024
	v_add_u32_e32 v51, 0x1a00, v51
	global_load_ushort v23, v51, s[88:89] offset:512
	global_load_ushort v177, v51, s[88:89] offset:1024
	v_add_u32_e32 v51, 0x1a00, v51
	global_load_ushort v24, v51, s[88:89] offset:512
	global_load_ushort v178, v51, s[88:89] offset:1024
	v_add_u32_e32 v51, 0x1a00, v51
	global_load_ushort v25, v51, s[88:89] offset:512
	global_load_ushort v179, v51, s[88:89] offset:1024
	v_add_u32_e32 v51, 0x1a00, v51
	v_add_u32_e32 v50, s5, v55
	s_cmp_ge_i32 s49, 1
	s_cselect_b64 s[60:61], -1, 0
	s_add_i32 s4, s49, 32
	s_cmp_lt_i32 s4, s45
	s_cselect_b64 s[6:7], -1, 0
	s_waitcnt vmcnt(32)
; __device__ __forceinline__ bf16_t f2bf(float f) { return (bf16_t)(pack2(f, 0.f) & 0xffffu); }
; __device__ __forceinline__ float bf2f(bf16_t h) { return __uint_as_float(((unsigned)h) << 16); }
; __device__ void hy_prep_tile(unsigned char* lds, const Params& p, int l, int b, int ck) {
;     ...
;     for (int q = 0; q < 32; ++q) {
;       const int tp = ts + q;
;       { const int tq = tp + 1 < L ? tp + 1 : L - 1; const float mk = tp + 1 < L ? 1.f : 0.f;
;         xn = mk * bf2f(z[(size_t)(rowbase + tq) * ZS + 256 + c]); vn = mk * bf2f(z[(size_t)(rowbase + tq) * ZS + 512 + c]); }
;       const float x1 = a0 * xp + a1 * xc + a2 * xn;
;       const float vv = v0 * vp + v1 * vc + v2 * vn;
;       uL[c * 66 + half * 32 + q] = f2bf(x1 * vv);
;       xp = xc; xc = xn; vp = vc; vc = vn;
;     }
	v_lshlrev_b32_e32 v0, 16, v0
	v_lshlrev_b32_e32 v154, 16, v154
	v_lshlrev_b32_e32 v1, 16, v1
	v_lshlrev_b32_e32 v155, 16, v155
	v_lshlrev_b32_e32 v2, 16, v2
	v_lshlrev_b32_e32 v156, 16, v156
	v_lshlrev_b32_e32 v3, 16, v3
	v_lshlrev_b32_e32 v157, 16, v157
	v_lshlrev_b32_e32 v4, 16, v4
	v_lshlrev_b32_e32 v158, 16, v158
	v_lshlrev_b32_e32 v5, 16, v5
	v_lshlrev_b32_e32 v159, 16, v159
	v_lshlrev_b32_e32 v6, 16, v6
	v_lshlrev_b32_e32 v160, 16, v160
	v_lshlrev_b32_e32 v7, 16, v7
	v_lshlrev_b32_e32 v161, 16, v161
	v_lshlrev_b32_e32 v8, 16, v8
	v_lshlrev_b32_e32 v162, 16, v162
	v_lshlrev_b32_e32 v9, 16, v9
	v_lshlrev_b32_e32 v163, 16, v163
	global_load_ushort v26, v51, s[88:89] offset:512
	global_load_ushort v180, v51, s[88:89] offset:1024
	v_add_u32_e32 v51, 0x1a00, v51
	global_load_ushort v27, v51, s[88:89] offset:512
	global_load_ushort v181, v51, s[88:89] offset:1024
	v_add_u32_e32 v51, 0x1a00, v51
	global_load_ushort v28, v51, s[88:89] offset:512
	global_load_ushort v182, v51, s[88:89] offset:1024
	v_add_u32_e32 v51, 0x1a00, v51
	global_load_ushort v29, v51, s[88:89] offset:512
	global_load_ushort v183, v51, s[88:89] offset:1024
	v_add_u32_e32 v51, 0x1a00, v51
	global_load_ushort v30, v51, s[88:89] offset:512
	global_load_ushort v184, v51, s[88:89] offset:1024
	v_add_u32_e32 v51, 0x1a00, v51
	global_load_ushort v31, v51, s[88:89] offset:512
	global_load_ushort v185, v51, s[88:89] offset:1024
	v_add_u32_e32 v51, 0x1a00, v51
	global_load_ushort v32, v51, s[88:89] offset:512
	global_load_ushort v186, v51, s[88:89] offset:1024
	global_load_ushort v33, v50, s[88:89] offset:512
	global_load_ushort v187, v50, s[88:89] offset:1024
	v_cndmask_b32_e64 v0, 0, v0, s[60:61]
	v_cndmask_b32_e64 v154, 0, v154, s[60:61]
	v_mul_f32_e32 v55, v199, v0
	v_mul_f32_e32 v52, v202, v154
	v_fmac_f32_e32 v55, v200, v1
	v_fmac_f32_e32 v52, v203, v155
	v_fmac_f32_e32 v55, v201, v2
	v_fmac_f32_e32 v52, v204, v156
	v_mul_f32_e32 v56, v55, v52
	v_mul_f32_e32 v55, v199, v1
	v_mul_f32_e32 v52, v202, v155
	v_fmac_f32_e32 v55, v200, v2
	v_fmac_f32_e32 v52, v203, v156
	v_fmac_f32_e32 v55, v201, v3
	v_fmac_f32_e32 v52, v204, v157
	v_mul_f32_e32 v57, v55, v52
	v_cvt_pk_bf16_f32 v34, v56, v57
	v_mul_f32_e32 v55, v199, v2
	v_mul_f32_e32 v52, v202, v156
	v_fmac_f32_e32 v55, v200, v3
	v_fmac_f32_e32 v52, v203, v157
	v_fmac_f32_e32 v55, v201, v4
	v_fmac_f32_e32 v52, v204, v158
	v_mul_f32_e32 v56, v55, v52
	v_mul_f32_e32 v55, v199, v3
	v_mul_f32_e32 v52, v202, v157
	v_fmac_f32_e32 v55, v200, v4
	v_fmac_f32_e32 v52, v203, v158
	v_fmac_f32_e32 v55, v201, v5
	v_fmac_f32_e32 v52, v204, v159
	v_mul_f32_e32 v57, v55, v52
	v_cvt_pk_bf16_f32 v35, v56, v57
	v_mul_f32_e32 v55, v199, v4
	v_mul_f32_e32 v52, v202, v158
	v_fmac_f32_e32 v55, v200, v5
	v_fmac_f32_e32 v52, v203, v159
	v_fmac_f32_e32 v55, v201, v6
	v_fmac_f32_e32 v52, v204, v160
	v_mul_f32_e32 v56, v55, v52
	v_mul_f32_e32 v55, v199, v5
	v_mul_f32_e32 v52, v202, v159
	v_fmac_f32_e32 v55, v200, v6
	v_fmac_f32_e32 v52, v203, v160
	v_fmac_f32_e32 v55, v201, v7
	v_fmac_f32_e32 v52, v204, v161
	v_mul_f32_e32 v57, v55, v52
	v_cvt_pk_bf16_f32 v36, v56, v57
	v_mul_f32_e32 v55, v199, v6
	v_mul_f32_e32 v52, v202, v160
	v_fmac_f32_e32 v55, v200, v7
	v_fmac_f32_e32 v52, v203, v161
	v_fmac_f32_e32 v55, v201, v8
	v_fmac_f32_e32 v52, v204, v162
	v_mul_f32_e32 v56, v55, v52
	v_mul_f32_e32 v55, v199, v7
	v_mul_f32_e32 v52, v202, v161
	v_fmac_f32_e32 v55, v200, v8
	v_fmac_f32_e32 v52, v203, v162
	v_fmac_f32_e32 v55, v201, v9
	v_fmac_f32_e32 v52, v204, v163
	v_mul_f32_e32 v57, v55, v52
	v_cvt_pk_bf16_f32 v37, v56, v57
	s_waitcnt vmcnt(32)
	v_lshlrev_b32_e32 v10, 16, v10
	v_lshlrev_b32_e32 v164, 16, v164
	v_lshlrev_b32_e32 v11, 16, v11
	v_lshlrev_b32_e32 v165, 16, v165
	v_lshlrev_b32_e32 v12, 16, v12
	v_lshlrev_b32_e32 v166, 16, v166
	v_lshlrev_b32_e32 v13, 16, v13
	v_lshlrev_b32_e32 v167, 16, v167
	v_lshlrev_b32_e32 v14, 16, v14
	v_lshlrev_b32_e32 v168, 16, v168
	v_lshlrev_b32_e32 v15, 16, v15
	v_lshlrev_b32_e32 v169, 16, v169
	v_lshlrev_b32_e32 v16, 16, v16
	v_lshlrev_b32_e32 v170, 16, v170
	v_lshlrev_b32_e32 v17, 16, v17
	v_lshlrev_b32_e32 v171, 16, v171
	v_mul_f32_e32 v55, v199, v8
	v_mul_f32_e32 v52, v202, v162
	v_fmac_f32_e32 v55, v200, v9
	v_fmac_f32_e32 v52, v203, v163
	v_fmac_f32_e32 v55, v201, v10
	v_fmac_f32_e32 v52, v204, v164
	v_mul_f32_e32 v56, v55, v52
	v_mul_f32_e32 v55, v199, v9
	v_mul_f32_e32 v52, v202, v163
	v_fmac_f32_e32 v55, v200, v10
	v_fmac_f32_e32 v52, v203, v164
	v_fmac_f32_e32 v55, v201, v11
	v_fmac_f32_e32 v52, v204, v165
	v_mul_f32_e32 v57, v55, v52
	v_cvt_pk_bf16_f32 v38, v56, v57
	v_mul_f32_e32 v55, v199, v10
	v_mul_f32_e32 v52, v202, v164
	v_fmac_f32_e32 v55, v200, v11
	v_fmac_f32_e32 v52, v203, v165
	v_fmac_f32_e32 v55, v201, v12
	v_fmac_f32_e32 v52, v204, v166
	v_mul_f32_e32 v56, v55, v52
	v_mul_f32_e32 v55, v199, v11
	v_mul_f32_e32 v52, v202, v165
	v_fmac_f32_e32 v55, v200, v12
	v_fmac_f32_e32 v52, v203, v166
	v_fmac_f32_e32 v55, v201, v13
	v_fmac_f32_e32 v52, v204, v167
	v_mul_f32_e32 v57, v55, v52
	v_cvt_pk_bf16_f32 v39, v56, v57
	v_mul_f32_e32 v55, v199, v12
	v_mul_f32_e32 v52, v202, v166
	v_fmac_f32_e32 v55, v200, v13
	v_fmac_f32_e32 v52, v203, v167
	v_fmac_f32_e32 v55, v201, v14
	v_fmac_f32_e32 v52, v204, v168
	v_mul_f32_e32 v56, v55, v52
	v_mul_f32_e32 v55, v199, v13
	v_mul_f32_e32 v52, v202, v167
	v_fmac_f32_e32 v55, v200, v14
	v_fmac_f32_e32 v52, v203, v168
	v_fmac_f32_e32 v55, v201, v15
	v_fmac_f32_e32 v52, v204, v169
	v_mul_f32_e32 v57, v55, v52
	v_cvt_pk_bf16_f32 v40, v56, v57
	v_mul_f32_e32 v55, v199, v14
	v_mul_f32_e32 v52, v202, v168
	v_fmac_f32_e32 v55, v200, v15
	v_fmac_f32_e32 v52, v203, v169
	v_fmac_f32_e32 v55, v201, v16
	v_fmac_f32_e32 v52, v204, v170
	v_mul_f32_e32 v56, v55, v52
	v_mul_f32_e32 v55, v199, v15
	v_mul_f32_e32 v52, v202, v169
	v_fmac_f32_e32 v55, v200, v16
	v_fmac_f32_e32 v52, v203, v170
	v_fmac_f32_e32 v55, v201, v17
	v_fmac_f32_e32 v52, v204, v171
	v_mul_f32_e32 v57, v55, v52
	v_cvt_pk_bf16_f32 v41, v56, v57
	s_waitcnt vmcnt(16)
; __device__ __forceinline__ bf16_t f2bf(float f) { return (bf16_t)(pack2(f, 0.f) & 0xffffu); }
; __device__ __forceinline__ float bf2f(bf16_t h) { return __uint_as_float(((unsigned)h) << 16); }
; __device__ void hy_prep_tile(unsigned char* lds, const Params& p, int l, int b, int ck) {
;     ...
;     for (int q = 0; q < 32; ++q) {
;       const int tp = ts + q;
;       { const int tq = tp + 1 < L ? tp + 1 : L - 1; const float mk = tp + 1 < L ? 1.f : 0.f;
;         xn = mk * bf2f(z[(size_t)(rowbase + tq) * ZS + 256 + c]); vn = mk * bf2f(z[(size_t)(rowbase + tq) * ZS + 512 + c]); }
;       const float x1 = a0 * xp + a1 * xc + a2 * xn;
;       const float vv = v0 * vp + v1 * vc + v2 * vn;
;       uL[c * 66 + half * 32 + q] = f2bf(x1 * vv);
;       xp = xc; xc = xn; vp = vc; vc = vn;
;     }
;   }
;   __syncthreads();
;   {
;     const int c = tid >> 1, hf = tid & 1;
;     const unsigned* src = (const unsigned*)(uL + c * 66 + hf * 32);
;     uint4* dst = (uint4*)(uT + ((size_t)c * 8 + b) * LTOT + posoff + t0 + hf * 32);
; #pragma unroll
;     for (int q = 0; q < 4; ++q) {
;       uint4 u; u.x = src[q * 4 + 0]; u.y = src[q * 4 + 1]; u.z = src[q * 4 + 2]; u.w = src[q * 4 + 3];
;       dst[q] = u;
;     }
;   }
	v_lshlrev_b32_e32 v18, 16, v18
	v_lshlrev_b32_e32 v172, 16, v172
	v_lshlrev_b32_e32 v19, 16, v19
	v_lshlrev_b32_e32 v173, 16, v173
	v_lshlrev_b32_e32 v20, 16, v20
	v_lshlrev_b32_e32 v174, 16, v174
	v_lshlrev_b32_e32 v21, 16, v21
	v_lshlrev_b32_e32 v175, 16, v175
	v_lshlrev_b32_e32 v22, 16, v22
	v_lshlrev_b32_e32 v176, 16, v176
	v_lshlrev_b32_e32 v23, 16, v23
	v_lshlrev_b32_e32 v177, 16, v177
	v_lshlrev_b32_e32 v24, 16, v24
	v_lshlrev_b32_e32 v178, 16, v178
	v_lshlrev_b32_e32 v25, 16, v25
	v_lshlrev_b32_e32 v179, 16, v179
	v_mul_f32_e32 v55, v199, v16
	v_mul_f32_e32 v52, v202, v170
	v_fmac_f32_e32 v55, v200, v17
	v_fmac_f32_e32 v52, v203, v171
	v_fmac_f32_e32 v55, v201, v18
	v_fmac_f32_e32 v52, v204, v172
	v_mul_f32_e32 v56, v55, v52
	v_mul_f32_e32 v55, v199, v17
	v_mul_f32_e32 v52, v202, v171
	v_fmac_f32_e32 v55, v200, v18
	v_fmac_f32_e32 v52, v203, v172
	v_fmac_f32_e32 v55, v201, v19
	v_fmac_f32_e32 v52, v204, v173
	v_mul_f32_e32 v57, v55, v52
	v_cvt_pk_bf16_f32 v42, v56, v57
	v_mul_f32_e32 v55, v199, v18
	v_mul_f32_e32 v52, v202, v172
	v_fmac_f32_e32 v55, v200, v19
	v_fmac_f32_e32 v52, v203, v173
	v_fmac_f32_e32 v55, v201, v20
	v_fmac_f32_e32 v52, v204, v174
	v_mul_f32_e32 v56, v55, v52
	v_mul_f32_e32 v55, v199, v19
	v_mul_f32_e32 v52, v202, v173
	v_fmac_f32_e32 v55, v200, v20
	v_fmac_f32_e32 v52, v203, v174
	v_fmac_f32_e32 v55, v201, v21
	v_fmac_f32_e32 v52, v204, v175
	v_mul_f32_e32 v57, v55, v52
	v_cvt_pk_bf16_f32 v43, v56, v57
	v_mul_f32_e32 v55, v199, v20
	v_mul_f32_e32 v52, v202, v174
	v_fmac_f32_e32 v55, v200, v21
	v_fmac_f32_e32 v52, v203, v175
	v_fmac_f32_e32 v55, v201, v22
	v_fmac_f32_e32 v52, v204, v176
	v_mul_f32_e32 v56, v55, v52
	v_mul_f32_e32 v55, v199, v21
	v_mul_f32_e32 v52, v202, v175
	v_fmac_f32_e32 v55, v200, v22
	v_fmac_f32_e32 v52, v203, v176
	v_fmac_f32_e32 v55, v201, v23
	v_fmac_f32_e32 v52, v204, v177
	v_mul_f32_e32 v57, v55, v52
	v_cvt_pk_bf16_f32 v44, v56, v57
	v_mul_f32_e32 v55, v199, v22
	v_mul_f32_e32 v52, v202, v176
	v_fmac_f32_e32 v55, v200, v23
	v_fmac_f32_e32 v52, v203, v177
	v_fmac_f32_e32 v55, v201, v24
	v_fmac_f32_e32 v52, v204, v178
	v_mul_f32_e32 v56, v55, v52
	v_mul_f32_e32 v55, v199, v23
	v_mul_f32_e32 v52, v202, v177
	v_fmac_f32_e32 v55, v200, v24
	v_fmac_f32_e32 v52, v203, v178
	v_fmac_f32_e32 v55, v201, v25
	v_fmac_f32_e32 v52, v204, v179
	v_mul_f32_e32 v57, v55, v52
	v_cvt_pk_bf16_f32 v45, v56, v57
	s_waitcnt vmcnt(0)
	v_lshlrev_b32_e32 v26, 16, v26
	v_lshlrev_b32_e32 v180, 16, v180
	v_lshlrev_b32_e32 v27, 16, v27
	v_lshlrev_b32_e32 v181, 16, v181
	v_lshlrev_b32_e32 v28, 16, v28
	v_lshlrev_b32_e32 v182, 16, v182
	v_lshlrev_b32_e32 v29, 16, v29
	v_lshlrev_b32_e32 v183, 16, v183
	v_lshlrev_b32_e32 v30, 16, v30
	v_lshlrev_b32_e32 v184, 16, v184
	v_lshlrev_b32_e32 v31, 16, v31
	v_lshlrev_b32_e32 v185, 16, v185
	v_lshlrev_b32_e32 v32, 16, v32
	v_lshlrev_b32_e32 v186, 16, v186
	v_lshlrev_b32_e32 v33, 16, v33
	v_lshlrev_b32_e32 v187, 16, v187
	v_cndmask_b32_e64 v33, 0, v33, s[6:7]
	v_cndmask_b32_e64 v187, 0, v187, s[6:7]
	v_mul_f32_e32 v55, v199, v24
	v_mul_f32_e32 v52, v202, v178
	v_fmac_f32_e32 v55, v200, v25
	v_fmac_f32_e32 v52, v203, v179
	v_fmac_f32_e32 v55, v201, v26
	v_fmac_f32_e32 v52, v204, v180
	v_mul_f32_e32 v56, v55, v52
	v_mul_f32_e32 v55, v199, v25
	v_mul_f32_e32 v52, v202, v179
	v_fmac_f32_e32 v55, v200, v26
	v_fmac_f32_e32 v52, v203, v180
	v_fmac_f32_e32 v55, v201, v27
	v_fmac_f32_e32 v52, v204, v181
	v_mul_f32_e32 v57, v55, v52
	v_cvt_pk_bf16_f32 v46, v56, v57
	v_mul_f32_e32 v55, v199, v26
	v_mul_f32_e32 v52, v202, v180
	v_fmac_f32_e32 v55, v200, v27
	v_fmac_f32_e32 v52, v203, v181
	v_fmac_f32_e32 v55, v201, v28
	v_fmac_f32_e32 v52, v204, v182
	v_mul_f32_e32 v56, v55, v52
	v_mul_f32_e32 v55, v199, v27
	v_mul_f32_e32 v52, v202, v181
	v_fmac_f32_e32 v55, v200, v28
	v_fmac_f32_e32 v52, v203, v182
	v_fmac_f32_e32 v55, v201, v29
	v_fmac_f32_e32 v52, v204, v183
	v_mul_f32_e32 v57, v55, v52
	v_cvt_pk_bf16_f32 v47, v56, v57
	v_mul_f32_e32 v55, v199, v28
	v_mul_f32_e32 v52, v202, v182
	v_fmac_f32_e32 v55, v200, v29
	v_fmac_f32_e32 v52, v203, v183
	v_fmac_f32_e32 v55, v201, v30
	v_fmac_f32_e32 v52, v204, v184
	v_mul_f32_e32 v56, v55, v52
	v_mul_f32_e32 v55, v199, v29
	v_mul_f32_e32 v52, v202, v183
	v_fmac_f32_e32 v55, v200, v30
	v_fmac_f32_e32 v52, v203, v184
	v_fmac_f32_e32 v55, v201, v31
	v_fmac_f32_e32 v52, v204, v185
	v_mul_f32_e32 v57, v55, v52
	v_cvt_pk_bf16_f32 v48, v56, v57
	v_mul_f32_e32 v55, v199, v30
	v_mul_f32_e32 v52, v202, v184
	v_fmac_f32_e32 v55, v200, v31
	v_fmac_f32_e32 v52, v203, v185
	v_fmac_f32_e32 v55, v201, v32
	v_fmac_f32_e32 v52, v204, v186
	v_mul_f32_e32 v56, v55, v52
	v_mul_f32_e32 v55, v199, v31
	v_mul_f32_e32 v52, v202, v185
	v_fmac_f32_e32 v55, v200, v32
	v_fmac_f32_e32 v52, v203, v186
	v_fmac_f32_e32 v55, v201, v33
	v_fmac_f32_e32 v52, v204, v187
	v_mul_f32_e32 v57, v55, v52
	v_cvt_pk_bf16_f32 v49, v56, v57
	global_store_dwordx4 v54, v[34:37], s[58:59]
	global_store_dwordx4 v54, v[38:41], s[58:59] offset:16
	global_store_dwordx4 v54, v[42:45], s[58:59] offset:32
	global_store_dwordx4 v54, v[46:49], s[58:59] offset:48
	s_mov_b64 s[0:1], 0
; __device__ __forceinline__ bf16_t f2bf(float f) { return (bf16_t)(pack2(f, 0.f) & 0xffffu); }
; __device__ __forceinline__ float bf2f(bf16_t h) { return __uint_as_float(((unsigned)h) << 16); }
; __device__ void rg_tile(unsigned char* lds, const Params& p, int l, int b, int ck, int hh, bool outmode) {
;     ...
;   const int chm_ = hh * 64 + (w & 3) * 16 + lr, dm_ = w >> 2;
;   const float br = p.in[22][(size_t)l * 1024 + (dm_ * 2 + 0) * 256 + chm_];
;   const float bi = p.in[22][(size_t)l * 1024 + (dm_ * 2 + 1) * 256 + chm_];
;   const float lam_ = p.in[23][(size_t)l * 512 + dm_ * 256 + chm_];
;   {
;     const int i = tid & 63, tq = tid >> 6;
;     const int ch = hh * 64 + i;
;     const float* wc = p.in[20] + (size_t)l * 4 * 256 + ch;
;     const float w0 = wc[0], w1 = wc[256], w2 = wc[512], w3 = wc[768];
; #pragma unroll
;     for (int ii = 0; ii < 8; ++ii) {
;       const int tt = tq * 8 + ii;
;       const int tp = t0 + tt;
;       const int tm1 = tp - 1 >= 0 ? tp - 1 : 0, tp1 = tp + 1 < L ? tp + 1 : L - 1, tp2 = tp + 2 < L ? tp + 2 : L - 1;
;       const float z0 = bf2f(z[(size_t)(rowbase + tm1) * ZS + 2816 + ch]);
;       const float z1 = bf2f(z[(size_t)(rowbase + tp) * ZS + 2816 + ch]);
;       const float z2 = bf2f(z[(size_t)(rowbase + tp1) * ZS + 2816 + ch]);
;       const float z3 = bf2f(z[(size_t)(rowbase + tp2) * ZS + 2816 + ch]);
;       float xr = w1 * z1;
;       xr += (tp - 1 >= 0 ? w0 : 0.f) * z0;
;       xr += (tp + 1 < L ? w2 : 0.f) * z2;
;       xr += (tp + 2 < L ? w3 : 0.f) * z3;
;       XR[tt * 65 + i] = xr;
;       XB[tt * 72 + i] = f2bf(xr);
;     }
;     const bf16_t* rgw = (const bf16_t*)(p.ws + OFF_RGW);
; #pragma unroll
;     for (int q = 0; q < 4; ++q) {
;       const int id = tid + 512 * q;
;       const int row = id >> 3, kc = id & 7;
;       *(uint4*)(WT + row * 72 + kc * 8) = *(const uint4*)(rgw + ((size_t)((l * 4 + (row >> 6)) * 4 + hh)) * 4096 + (row & 63) * 64 + kc * 8);
; __device__ void hy_prep_tile(unsigned char* lds, const Params& p, int l, int b, int ck) {
;     ...
;   __syncthreads();
.LBB0_326:
	s_andn2_b64 vcc, exec, s[0:1]
	s_cbranch_vccnz .LBB0_330
	s_add_i32 s0, s20, 0xfffffdc0
	s_lshr_b32 s1, s0, 2
	s_mul_i32 s2, s1, 0xe38f
	s_lshr_b32 s2, s2, 21
	s_mul_i32 s2, s2, 36
	s_sub_i32 s1, s1, s2
	s_mul_i32 s0, s0, 0xe38f
	s_and_b32 s2, s1, 0xffff
	s_lshr_b32 s3, s0, 23
	v_mov_b32_e32 v29, v195
	s_lshl_b32 s0, s2, 6
	s_lshl_b32 s4, s3, 8
	s_and_b32 s5, s20, 3
	s_add_i32 s1, s0, 0xffffff00
	v_ashrrev_i32_e32 v28, 6, v29
	s_add_i32 s6, s4, 0x4000
	s_lshl_b32 s7, s3, 11
	v_and_b32_e32 v6, 15, v29
	s_cmp_lt_u32 s2, 4
	s_movk_i32 s4, 0x800
	v_lshlrev_b32_e32 v0, 4, v28
	v_ashrrev_i32_e32 v35, 8, v29
	s_cselect_b32 s4, 0x100, s4
	s_cselect_b32 s9, s0, s1
	s_cselect_b32 s6, s6, s7
	v_readfirstlane_b32 s44, v195
	s_mov_b32 s47, s4
	s_mov_b32 s48, s6
	s_mov_b32 s49, s9
	s_lshl_b32 s50, s5, 7
	s_lshr_b32 s44, s44, 6
	s_lshl_b32 s45, s44, 3
	s_add_i32 s45, s45, s49
	s_add_i32 s46, s47, -1
	s_addk_i32 s50, 0x1600
	v_and_b32_e32 v185, 63, v195
	v_lshl_add_u32 v180, v185, 1, s50
	v_readlane_b32 s52, v254, 3
	v_readlane_b32 s53, v254, 4
	s_lshl_b32 s51, s5, 8
	v_lshl_add_u32 v181, v185, 2, s51
	s_nop 2
	global_load_dword v165, v181, s[52:53]
	s_nop 1
	global_load_dword v166, v181, s[52:53] offset:1024
	s_nop 0
	global_load_dword v167, v181, s[52:53] offset:2048
	global_load_dword v168, v181, s[52:53] offset:3072
	s_add_i32 s54, s45, s48
	s_mul_i32 s54, s54, 0x1a00
	v_add_u32_e32 v181, s54, v180
	s_add_i32 s55, s45, -1
	s_max_i32 s55, s55, 0
	s_add_i32 s55, s55, s48
	s_mul_i32 s55, s55, 0x1a00
	v_add_u32_e32 v184, s55, v180
	global_load_ushort v154, v184, s[88:89]
	global_load_ushort v155, v181, s[88:89]
	v_add_u32_e32 v181, 0x1a00, v181
	global_load_ushort v156, v181, s[88:89]
	v_add_u32_e32 v181, 0x1a00, v181
	global_load_ushort v157, v181, s[88:89]
	v_add_u32_e32 v181, 0x1a00, v181
	global_load_ushort v158, v181, s[88:89]
	v_add_u32_e32 v181, 0x1a00, v181
	global_load_ushort v159, v181, s[88:89]
	v_add_u32_e32 v181, 0x1a00, v181
	global_load_ushort v160, v181, s[88:89]
	v_add_u32_e32 v181, 0x1a00, v181
	global_load_ushort v161, v181, s[88:89]
	v_add_u32_e32 v181, 0x1a00, v181
	global_load_ushort v162, v181, s[88:89]
	s_add_i32 s55, s45, 8
	s_min_i32 s55, s55, s46
	s_add_i32 s55, s55, s48
	s_mul_i32 s55, s55, 0x1a00
	v_add_u32_e32 v184, s55, v180
	global_load_ushort v163, v184, s[88:89]
	s_add_i32 s55, s45, 9
	s_min_i32 s55, s55, s46
	s_add_i32 s55, s55, s48
	s_mul_i32 s55, s55, 0x1a00
	v_add_u32_e32 v184, s55, v180
	global_load_ushort v164, v184, s[88:89]
	s_mul_i32 s55, s44, 0x820
	v_lshl_add_u32 v182, v185, 2, s55
	s_mul_i32 s55, s44, 0x480
	v_lshl_add_u32 v183, v185, 1, s55
	s_lshl_b32 s0, s5, 6
	v_and_or_b32 v34, v0, 48, v6
	v_lshlrev_b32_e32 v0, 9, v35
	v_or_b32_e32 v2, s0, v34
	v_ashrrev_i32_e32 v1, 31, v0
	v_lshl_add_u64 v[0:1], v[0:1], 2, s[16:17]
	v_lshlrev_b32_e32 v192, 2, v2
	v_lshl_or_b32 v7, v35, 1, 1
	v_lshl_add_u64 v[2:3], v[0:1], 0, v[192:193]
	v_lshlrev_b32_e32 v0, 8, v7
	v_ashrrev_i32_e32 v1, 31, v0
	v_lshl_add_u64 v[0:1], v[0:1], 2, s[16:17]
	v_lshl_add_u64 v[4:5], v[0:1], 0, v[192:193]
	v_and_b32_e32 v0, 0xffffff00, v29
	v_readlane_b32 s22, v254, 1
	v_lshlrev_b32_e32 v18, 3, v28
	v_ashrrev_i32_e32 v1, 31, v0
	v_readlane_b32 s23, v254, 2
	v_add_u32_e32 v26, s9, v18
	v_and_b32_e32 v31, 63, v29
	v_lshl_add_u64 v[0:1], v[0:1], 2, s[22:23]
	v_lshl_add_u64 v[12:13], v[0:1], 0, v[192:193]
	s_add_i32 s8, s6, -1
	v_or_b32_e32 v30, s0, v31
	v_mov_b64_e32 v[0:1], s[88:89]
	v_lshlrev_b32_e32 v192, 1, v30
	s_add_i32 s7, s4, -1
	s_movk_i32 s21, 0x1000
	v_readlane_b32 s0, v254, 3
	v_lshlrev_b32_e32 v19, 2, v30
	v_readlane_b32 s1, v254, 4
	s_nop 4
	global_load_dword v10, v19, s[0:1] offset:1024
	s_nop 3
	global_load_dword v8, v19, s[0:1] offset:2048
	s_nop 2
	global_load_dword v9, v19, s[0:1] offset:3072
	s_nop 1
	global_load_dword v11, v19, s[0:1]
	global_load_dword v33, v[2:3], off
	global_load_dword v32, v[4:5], off
	global_load_dword v16, v[12:13], off
	s_movk_i32 s22, 0x104
	s_movk_i32 s9, 0x90
	v_or_b32_e32 v49, 7, v26
	v_add_u32_e32 v50, 8, v26
	v_add_u32_e32 v51, 9, v26
	v_ashrrev_i32_e32 v58, 3, v29
	v_min_i32_e32 v38, s7, v51
	v_min_i32_e32 v24, s7, v50
	v_add_u32_e32 v3, s6, v24
	v_mad_i64_i32 v[24:25], s[0:1], v3, s92, v[0:1]
	v_lshl_add_u64 v[24:25], v[24:25], 0, v[192:193]
	v_max_i32_e32 v3, 1, v49
	v_add_co_u32_e64 v24, s[0:1], s21, v24
	v_add_u32_e32 v3, s8, v3
	s_nop 0
	v_addc_co_u32_e64 v25, s[0:1], 0, v25, s[0:1]
	v_mad_u64_u32 v[26:27], s[0:1], v3, s92, v[0:1]
	v_lshl_add_u64 v[26:27], v[26:27], 0, v[192:193]
	v_add_co_u32_e64 v26, s[0:1], s21, v26
	v_add_u32_e32 v3, s6, v49
	s_nop 0
	v_addc_co_u32_e64 v27, s[0:1], 0, v27, s[0:1]
	v_mad_i64_i32 v[36:37], s[0:1], v3, s92, v[0:1]
	v_lshl_add_u64 v[36:37], v[36:37], 0, v[192:193]
	v_add_co_u32_e64 v36, s[0:1], s21, v36
	s_nop 1
	v_addc_co_u32_e64 v37, s[0:1], 0, v37, s[0:1]
	global_load_ushort v56, v[24:25], off offset:1536
	global_load_ushort v57, v[26:27], off offset:1536
	global_load_ushort v37, v[36:37], off offset:1536
	v_add_u32_e32 v12, s6, v38
	v_mad_i64_i32 v[0:1], s[0:1], v12, s92, v[0:1]
	v_lshl_add_u64 v[0:1], v[0:1], 0, v[192:193]
	v_add_co_u32_e64 v0, s[0:1], s21, v0
	v_lshlrev_b32_e32 v12, 4, v29
	s_nop 0
	v_addc_co_u32_e64 v1, s[0:1], 0, v1, s[0:1]
	v_readlane_b32 s0, v254, 5
	v_ashrrev_i32_e32 v36, 7, v29
	s_or_b32 s0, s5, s0
	v_and_b32_e32 v26, 0x70, v12
	v_and_b32_e32 v12, -4, v36
	v_add_u32_e32 v12, s0, v12
	v_ashrrev_i32_e32 v13, 31, v12
	v_readlane_b32 s6, v251, 22
	v_lshlrev_b64 v[12:13], 13, v[12:13]
	v_readlane_b32 s7, v251, 23
	v_lshlrev_b32_e32 v14, 7, v58
	v_and_b32_e32 v192, 0x1f80, v14
	v_lshl_add_u64 v[12:13], s[6:7], 0, v[12:13]
; __device__ __forceinline__ bf16_t f2bf(float f) { return (bf16_t)(pack2(f, 0.f) & 0xffffu); }
; __device__ __forceinline__ float bf2f(bf16_t h) { return __uint_as_float(((unsigned)h) << 16); }
; __device__ void rg_tile(unsigned char* lds, const Params& p, int l, int b, int ck, int hh, bool outmode) {
;     ...
;     const int i = tid & 63, tq = tid >> 6;
;     const int ch = hh * 64 + i;
;     const float* wc = p.in[20] + (size_t)l * 4 * 256 + ch;
;     const float w0 = wc[0], w1 = wc[256], w2 = wc[512], w3 = wc[768];
; #pragma unroll
;     for (int ii = 0; ii < 8; ++ii) {
;       const int tt = tq * 8 + ii;
;       const int tp = t0 + tt;
;       const int tm1 = tp - 1 >= 0 ? tp - 1 : 0, tp1 = tp + 1 < L ? tp + 1 : L - 1, tp2 = tp + 2 < L ? tp + 2 : L - 1;
;       const float z0 = bf2f(z[(size_t)(rowbase + tm1) * ZS + 2816 + ch]);
;       const float z1 = bf2f(z[(size_t)(rowbase + tp) * ZS + 2816 + ch]);
;       const float z2 = bf2f(z[(size_t)(rowbase + tp1) * ZS + 2816 + ch]);
;       const float z3 = bf2f(z[(size_t)(rowbase + tp2) * ZS + 2816 + ch]);
;       float xr = w1 * z1;
;       xr += (tp - 1 >= 0 ? w0 : 0.f) * z0;
;       xr += (tp + 1 < L ? w2 : 0.f) * z2;
;       xr += (tp + 2 < L ? w3 : 0.f) * z3;
;       XR[tt * 65 + i] = xr;
;       XB[tt * 72 + i] = f2bf(xr);
;     }
;     const bf16_t* rgw = (const bf16_t*)(p.ws + OFF_RGW);
; #pragma unroll
;     for (int q = 0; q < 4; ++q) {
;       const int id = tid + 512 * q;
;       const int row = id >> 3, kc = id & 7;
;       *(uint4*)(WT + row * 72 + kc * 8) = *(const uint4*)(rgw + ((size_t)((l * 4 + (row >> 6)) * 4 + hh)) * 4096 + (row & 63) * 64 + kc * 8);
;     }
;   }
;   __syncthreads();
	v_lshl_add_u64 v[12:13], v[12:13], 0, v[192:193]
	v_mov_b32_e32 v27, v193
	v_lshl_add_u64 v[12:13], v[12:13], 0, v[26:27]
	global_load_ushort v59, v[0:1], off offset:1536
	global_load_dwordx4 v[12:15], v[12:13], off
	v_add_u32_e32 v0, 0x200, v29
	v_ashrrev_i32_e32 v60, 3, v0
	v_lshlrev_b32_e32 v18, 7, v60
	v_ashrrev_i32_e32 v0, 7, v0
	v_and_b32_e32 v192, 0x1f80, v18
	v_add_u32_e32 v18, 0x400, v29
	v_and_b32_e32 v0, -4, v0
	v_ashrrev_i32_e32 v61, 3, v18
	v_ashrrev_i32_e32 v18, 7, v18
	v_add_u32_e32 v0, s0, v0
	v_and_b32_e32 v18, -4, v18
	v_ashrrev_i32_e32 v1, 31, v0
	v_add_u32_e32 v18, s0, v18
	v_lshlrev_b64 v[0:1], 13, v[0:1]
	v_ashrrev_i32_e32 v19, 31, v18
	v_lshl_add_u64 v[0:1], s[6:7], 0, v[0:1]
	v_lshlrev_b64 v[18:19], 13, v[18:19]
	v_lshlrev_b32_e32 v20, 7, v61
	v_lshl_add_u64 v[0:1], v[0:1], 0, v[192:193]
	v_lshl_add_u64 v[18:19], s[6:7], 0, v[18:19]
	v_and_b32_e32 v192, 0x1f80, v20
	v_lshl_add_u64 v[18:19], v[18:19], 0, v[192:193]
	v_lshl_add_u64 v[0:1], v[0:1], 0, v[26:27]
	v_lshl_add_u64 v[22:23], v[18:19], 0, v[26:27]
	global_load_dwordx4 v[18:21], v[0:1], off
	global_load_dwordx4 v[22:25], v[22:23], off
	v_add_u32_e32 v0, 0x600, v29
	v_ashrrev_i32_e32 v62, 3, v0
	v_ashrrev_i32_e32 v0, 7, v0
	v_and_b32_e32 v0, -4, v0
	v_add_u32_e32 v0, s0, v0
	v_ashrrev_i32_e32 v1, 31, v0
	v_lshlrev_b64 v[0:1], 13, v[0:1]
	v_lshlrev_b32_e32 v38, 7, v62
	v_lshl_add_u64 v[0:1], s[6:7], 0, v[0:1]
	v_and_b32_e32 v192, 0x1f80, v38
	v_lshl_add_u64 v[0:1], v[0:1], 0, v[192:193]
	v_lshl_add_u64 v[0:1], v[0:1], 0, v[26:27]
	global_load_dwordx4 v[38:41], v[0:1], off
	v_cmp_gt_i32_e32 vcc, s4, v50
	s_waitcnt vmcnt(0)
	v_lshlrev_b32_e32 v27, 16, v56
	v_lshlrev_b32_e32 v1, 16, v37
	v_cmp_lt_i32_e64 s[0:1], 0, v49
	v_lshlrev_b32_e32 v0, 16, v57
	v_mul_f32_e32 v1, v10, v1
	v_cndmask_b32_e64 v5, 0, v11, s[0:1]
	v_fmac_f32_e32 v1, v5, v0
	v_cndmask_b32_e32 v0, 0, v8, vcc
	v_cmp_gt_i32_e32 vcc, s4, v51
	v_lshlrev_b32_e32 v3, 16, v59
	v_fmac_f32_e32 v1, v0, v27
	v_cndmask_b32_e32 v0, 0, v9, vcc
	v_fmac_f32_e32 v1, v0, v3
	v_add_u32_e32 v0, 0, v26
	v_mad_u64_u32 v[2:3], s[0:1], v58, s9, v[0:1]
	ds_write_b128 v2, v[12:15] offset:25856
	v_mad_u64_u32 v[2:3], s[0:1], v60, s9, v[0:1]
	ds_write_b128 v2, v[18:21] offset:25856
	v_mad_u64_u32 v[2:3], s[0:1], v61, s9, v[0:1]
	v_mad_u64_u32 v[0:1], s[0:1], v62, s9, v[0:1]
	ds_write_b128 v2, v[22:25] offset:25856
	ds_write_b128 v0, v[38:41] offset:25856
	v_and_b32_e32 v0, 48, v29
	v_add_u32_e32 v0, 0, v0
	v_mad_u32_u24 v17, v6, s9, v0
	s_waitcnt vmcnt(0)
	v_lshlrev_b32_e32 v154, 16, v154
	v_lshlrev_b32_e32 v155, 16, v155
	v_lshlrev_b32_e32 v156, 16, v156
	v_lshlrev_b32_e32 v157, 16, v157
	v_lshlrev_b32_e32 v158, 16, v158
	v_lshlrev_b32_e32 v159, 16, v159
	v_lshlrev_b32_e32 v160, 16, v160
	v_lshlrev_b32_e32 v161, 16, v161
	v_lshlrev_b32_e32 v162, 16, v162
	v_lshlrev_b32_e32 v163, 16, v163
	v_lshlrev_b32_e32 v164, 16, v164
	s_cmp_ge_i32 s45, 1
	s_cselect_b64 s[56:57], -1, 0
	s_add_i32 s55, s45, 8
	s_cmp_lt_i32 s55, s47
	s_cselect_b64 s[58:59], -1, 0
	v_cndmask_b32_e64 v169, 0, v165, s[56:57]
	v_cndmask_b32_e64 v170, 0, v167, s[58:59]
	v_cndmask_b32_e64 v171, 0, v168, s[58:59]
	v_mul_f32_e32 v172, v166, v155
	v_fmac_f32_e32 v172, v169, v154
	v_fmac_f32_e32 v172, v167, v156
	v_fmac_f32_e32 v172, v168, v157
	v_mul_f32_e32 v173, v166, v156
	v_fmac_f32_e32 v173, v165, v155
	v_fmac_f32_e32 v173, v167, v157
	v_fmac_f32_e32 v173, v168, v158
	v_mul_f32_e32 v174, v166, v157
	v_fmac_f32_e32 v174, v165, v156
	v_fmac_f32_e32 v174, v167, v158
	v_fmac_f32_e32 v174, v168, v159
	v_mul_f32_e32 v175, v166, v158
	v_fmac_f32_e32 v175, v165, v157
	v_fmac_f32_e32 v175, v167, v159
	v_fmac_f32_e32 v175, v168, v160
	v_mul_f32_e32 v176, v166, v159
	v_fmac_f32_e32 v176, v165, v158
	v_fmac_f32_e32 v176, v167, v160
	v_fmac_f32_e32 v176, v168, v161
	v_mul_f32_e32 v177, v166, v160
	v_fmac_f32_e32 v177, v165, v159
	v_fmac_f32_e32 v177, v167, v161
	v_fmac_f32_e32 v177, v168, v162
	v_mul_f32_e32 v178, v166, v161
	v_fmac_f32_e32 v178, v165, v160
	v_fmac_f32_e32 v178, v167, v162
	v_fmac_f32_e32 v178, v171, v163
	v_mul_f32_e32 v179, v166, v162
	v_fmac_f32_e32 v179, v165, v161
	v_fmac_f32_e32 v179, v170, v163
	v_fmac_f32_e32 v179, v171, v164
	v_cvt_pk_bf16_f32 v184, v172, v172
	ds_write_b32 v182, v172
	ds_write_b16 v183, v184 offset:16640
	v_cvt_pk_bf16_f32 v184, v173, v173
	ds_write_b32 v182, v173 offset:260
	ds_write_b16 v183, v184 offset:16784
	v_cvt_pk_bf16_f32 v184, v174, v174
	ds_write_b32 v182, v174 offset:520
	ds_write_b16 v183, v184 offset:16928
	v_cvt_pk_bf16_f32 v184, v175, v175
	ds_write_b32 v182, v175 offset:780
	ds_write_b16 v183, v184 offset:17072
	v_cvt_pk_bf16_f32 v184, v176, v176
	ds_write_b32 v182, v176 offset:1040
	ds_write_b16 v183, v184 offset:17216
	v_cvt_pk_bf16_f32 v184, v177, v177
	ds_write_b32 v182, v177 offset:1300
	ds_write_b16 v183, v184 offset:17360
	v_cvt_pk_bf16_f32 v184, v178, v178
	ds_write_b32 v182, v178 offset:1560
	ds_write_b16 v183, v184 offset:17504
	v_cvt_pk_bf16_f32 v184, v179, v179
	ds_write_b32 v182, v179 offset:1820
	ds_write_b16 v183, v184 offset:17648
	s_waitcnt lgkmcnt(0)
	s_barrier
; __device__ __forceinline__ float fexp(float x) { return __expf(x); }
; __device__ __forceinline__ float sigm(float x) { return frcp(1.f + fexp(-x)); }
; __device__ __forceinline__ float softplusf(float x) { return fmaxf(x, 0.f) + __logf(1.f + fexp(-fabsf(x))); }
; __device__ void rg_tile(unsigned char* lds, const Params& p, int l, int b, int ck, int hh, bool outmode) {
;     ...
;   {
;     const int d = w >> 2, jf = w & 3;
;     f32x4 ar[4], ai[4];
; #pragma unroll
;     for (int i = 0; i < 4; ++i) { ar[i] = (f32x4){0.f, 0.f, 0.f, 0.f}; ai[i] = (f32x4){0.f, 0.f, 0.f, 0.f}; }
; #pragma unroll
;     for (int ks = 0; ks < 2; ++ks) {
;       const bf16x8 wr = ldfrag(WT + ((d * 2 + 0) * 64 + jf * 16 + lr) * 72 + ks * 32 + lg * 8);
;       const bf16x8 wi = ldfrag(WT + ((d * 2 + 1) * 64 + jf * 16 + lr) * 72 + ks * 32 + lg * 8);
; #pragma unroll
;       for (int tf = 0; tf < 4; ++tf) {
;         const bf16x8 xf = ldfrag(XB + (tf * 16 + lr) * 72 + ks * 32 + lg * 8);
;         ar[tf] = mfma16(xf, wr, ar[tf]);
;         ai[tf] = mfma16(xf, wi, ai[tf]);
;       }
;     }
;     const int j = jf * 16 + lr;
;     const int ch = hh * 64 + j;
;     const float sp = softplusf(-lam_);
; #pragma unroll
;     for (int tf = 0; tf < 4; ++tf)
; #pragma unroll
;       for (int jj = 0; jj < 4; ++jj) {
;         const int tt = tf * 16 + lg * 4 + jj;
;         const float r = sigm(ar[tf][jj] + br);
;         const float ig = sigm(ai[tf][jj] + bi);
;         const float la = -8.0f * r * sp;
;         const float a = fexp(la);
;         const float bq = __builtin_amdgcn_sqrtf(fmaxf(1.f - a * a, 0.f)) * ig * XR[tt * 65 + j];
;         AA[(d * 64 + tt) * 64 + j] = a;
;         BQ[(d * 64 + tt) * 64 + j] = bq;
;       }
	ds_read_b128 v[18:21], v17 offset:16640
	v_lshl_or_b32 v1, v35, 7, v34
	v_mad_u64_u32 v[2:3], s[0:1], v1, s9, v[0:1]
	v_lshl_or_b32 v1, v7, 6, v34
	ds_read_b128 v[12:15], v2 offset:25856
	v_mad_u64_u32 v[0:1], s[0:1], v1, s9, v[0:1]
	ds_read_b128 v[4:7], v2 offset:25920
	ds_read_b128 v[22:25], v17 offset:16704
	ds_read_b128 v[8:11], v0 offset:25856
	ds_read_b128 v[0:3], v0 offset:25920
	s_mov_b32 s0, 0xbfb8aa3b
	v_mul_f32_e64 v26, |v16|, s0
	s_waitcnt lgkmcnt(4)
	v_mfma_f32_16x16x32_bf16 v[38:41], v[18:21], v[12:15], 0
	v_exp_f32_e32 v26, v26
	s_mov_b32 s0, 0x800000
	v_max_f32_e64 v16, -v16, -v16
	s_waitcnt lgkmcnt(1)
	v_mfma_f32_16x16x32_bf16 v[18:21], v[18:21], v[8:11], 0
	v_max_f32_e32 v16, 0, v16
	v_bfe_u32 v62, v29, 4, 2
	ds_read_b128 v[42:45], v17 offset:18944
	ds_read_b128 v[46:49], v17 offset:19008
	s_waitcnt lgkmcnt(2)
	v_mfma_f32_16x16x32_bf16 v[54:57], v[22:25], v[0:3], v[18:21]
	v_lshlrev_b32_e32 v35, 12, v35
	s_nop 1
	v_add_f32_e32 v18, 1.0, v26
	v_cmp_gt_f32_e32 vcc, s0, v18
	v_mfma_f32_16x16x32_bf16 v[38:41], v[22:25], v[4:7], v[38:41]
	s_mov_b32 s0, 0x3f317217
	v_cndmask_b32_e64 v19, 0, 32, vcc
	v_ldexp_f32 v18, v18, v19
	v_log_f32_e32 v18, v18
	v_mov_b32_e32 v20, 0x41b17218
	v_cndmask_b32_e32 v20, 0, v20, vcc
	s_nop 1
	v_add_f32_e32 v39, v33, v39
	v_mul_f32_e32 v19, 0x3f317217, v18
	v_fma_f32 v19, v18, s0, -v19
	v_fmac_f32_e32 v19, 0x3377d1cf, v18
	s_mov_b32 s0, 0x7f800000
	v_fmac_f32_e32 v19, 0x3f317217, v18
	v_cmp_lt_f32_e64 s[0:1], |v18|, s0
	ds_read_b128 v[58:61], v17 offset:21248
	ds_read_b128 v[24:27], v17 offset:21312
	v_cndmask_b32_e64 v18, v18, v19, s[0:1]
	v_add_f32_e32 v19, v33, v38
	v_mul_f32_e32 v19, 0xbfb8aa3b, v19
	v_exp_f32_e32 v19, v19
	v_sub_f32_e32 v18, v18, v20
	v_add_f32_e32 v37, v16, v18
	v_add_f32_e32 v18, v32, v54
	v_add_f32_e32 v16, 1.0, v19
	v_rcp_f32_e32 v16, v16
	v_mul_f32_e32 v18, 0xbfb8aa3b, v18
	v_exp_f32_e32 v18, v18
	v_lshl_add_u32 v54, v34, 2, 0
	v_mul_f32_e32 v16, 0xc1000000, v16
	v_mul_f32_e32 v16, v37, v16
	v_mul_f32_e32 v16, 0x3fb8aa3b, v16
	v_exp_f32_e32 v38, v16
	v_add_f32_e32 v16, 1.0, v18
	v_rcp_f32_e32 v63, v16
	s_movk_i32 s0, 0x410
	v_fma_f32 v16, -v38, v38, 1.0
	v_max_f32_e32 v16, 0, v16
	v_sqrt_f32_e32 v64, v16
	v_mad_u32_u24 v16, v62, s0, v54
	ds_read_b32 v65, v16
	ds_read_b128 v[20:23], v17 offset:23552
	ds_read_b128 v[16:19], v17 offset:23616
	v_mul_f32_e32 v39, 0xbfb8aa3b, v39
	v_mul_f32_e32 v63, v63, v64
	v_lshlrev_b32_e32 v64, 8, v62
	v_or3_b32 v64, v64, v35, v34
	v_exp_f32_e32 v39, v39
	v_lshlrev_b32_e32 v64, 2, v64
	s_waitcnt lgkmcnt(2)
	v_mul_f32_e32 v63, v65, v63
	v_add_u32_e32 v65, 0, v64
	v_readlane_b32 s0, v253, 37
	ds_write_b32 v65, v38 offset:62720
	v_mfma_f32_16x16x32_bf16 v[50:53], v[42:45], v[12:15], 0
	v_add_u32_e32 v38, s0, v64
	ds_write_b32 v38, v63
	v_add_f32_e32 v38, 1.0, v39
	v_add_f32_e32 v39, v32, v55
	v_lshl_or_b32 v55, v62, 2, 1
	v_rcp_f32_e32 v38, v38
	v_mad_u32_u24 v54, v55, s22, v54
	v_lshlrev_b32_e32 v55, 6, v55
	v_or3_b32 v34, v55, v35, v34
	v_add_f32_e32 v35, v33, v40
	v_mul_f32_e32 v35, 0xbfb8aa3b, v35
	v_exp_f32_e32 v35, v35
	v_mul_f32_e32 v38, 0xc1000000, v38
	v_mul_f32_e32 v38, v37, v38
	v_mul_f32_e32 v38, 0x3fb8aa3b, v38
	v_mul_f32_e32 v39, 0xbfb8aa3b, v39
	v_exp_f32_e32 v38, v38
	v_add_f32_e32 v35, 1.0, v35
	v_exp_f32_e32 v39, v39
	v_rcp_f32_e32 v35, v35
	v_fma_f32 v62, -v38, v38, 1.0
	v_lshlrev_b32_e32 v34, 2, v34
	v_add_f32_e32 v39, 1.0, v39
	v_max_f32_e32 v62, 0, v62
	v_add_u32_e32 v40, 0, v34
	v_mul_f32_e32 v35, 0xc1000000, v35
	v_rcp_f32_e32 v39, v39
	v_sqrt_f32_e32 v62, v62
	ds_read_b32 v63, v54
	ds_write_b32 v40, v38 offset:62720
	v_add_f32_e32 v38, v32, v56
	v_mul_f32_e32 v35, v37, v35
	v_mul_f32_e32 v38, 0xbfb8aa3b, v38
	v_mul_f32_e32 v35, 0x3fb8aa3b, v35
	v_exp_f32_e32 v38, v38
	v_exp_f32_e32 v35, v35
	v_mul_f32_e32 v39, v39, v62
	s_waitcnt lgkmcnt(1)
	v_mul_f32_e32 v39, v63, v39
	v_add_u32_e32 v34, s0, v34
	ds_write_b32 v34, v39
	v_add_f32_e32 v34, 1.0, v38
	v_fma_f32 v38, -v35, v35, 1.0
	v_max_f32_e32 v38, 0, v38
	v_rcp_f32_e32 v34, v34
	v_sqrt_f32_e32 v38, v38
	ds_read_b32 v39, v54 offset:260
	v_mfma_f32_16x16x32_bf16 v[42:45], v[42:45], v[8:11], 0
	v_mul_f32_e32 v34, v34, v38
	v_or_b32_e32 v38, 0x200, v64
	s_waitcnt lgkmcnt(0)
	v_mul_f32_e32 v34, v34, v39
	v_add_f32_e32 v39, v33, v41
	v_mul_f32_e32 v39, 0xbfb8aa3b, v39
	v_exp_f32_e32 v39, v39
	v_add_u32_e32 v40, 0, v38
	ds_write_b32 v40, v35 offset:62720
	v_add_u32_e32 v35, s0, v38
	v_add_f32_e32 v38, 1.0, v39
	v_rcp_f32_e32 v38, v38
	v_add_f32_e32 v39, v32, v57
	v_mul_f32_e32 v39, 0xbfb8aa3b, v39
	v_mfma_f32_16x16x32_bf16 v[50:53], v[46:49], v[4:7], v[50:53]
	v_exp_f32_e32 v39, v39
	v_mul_f32_e32 v38, 0xc1000000, v38
	v_mul_f32_e32 v38, v37, v38
	v_mul_f32_e32 v38, 0x3fb8aa3b, v38
	v_exp_f32_e32 v55, v38
	ds_write_b32 v35, v34
	v_add_f32_e32 v34, 1.0, v39
	v_mfma_f32_16x16x32_bf16 v[38:41], v[46:49], v[0:3], v[42:45]
	v_fma_f32 v35, -v55, v55, 1.0
	v_max_f32_e32 v35, 0, v35
	v_rcp_f32_e32 v34, v34
	v_add_f32_e32 v42, v33, v50
	v_mul_f32_e32 v42, 0xbfb8aa3b, v42
	v_exp_f32_e32 v42, v42
	v_sqrt_f32_e32 v35, v35
	ds_read_b32 v56, v54 offset:520
	v_add_f32_e32 v38, v32, v38
	v_add_f32_e32 v42, 1.0, v42
	v_rcp_f32_e32 v42, v42
	v_mul_f32_e32 v38, 0xbfb8aa3b, v38
	v_exp_f32_e32 v38, v38
	v_mul_f32_e32 v34, v34, v35
	v_mul_f32_e32 v42, 0xc1000000, v42
	v_mul_f32_e32 v42, v37, v42
	v_mul_f32_e32 v42, 0x3fb8aa3b, v42
	v_exp_f32_e32 v46, v42
	v_or_b32_e32 v35, 0x300, v64
	s_waitcnt lgkmcnt(0)
; __device__ __forceinline__ float fexp(float x) { return __expf(x); }
; __device__ __forceinline__ float sigm(float x) { return frcp(1.f + fexp(-x)); }
; __device__ void rg_tile(unsigned char* lds, const Params& p, int l, int b, int ck, int hh, bool outmode) {
;     ...
; #pragma unroll
;     for (int tf = 0; tf < 4; ++tf)
; #pragma unroll
;       for (int jj = 0; jj < 4; ++jj) {
;         const int tt = tf * 16 + lg * 4 + jj;
;         const float r = sigm(ar[tf][jj] + br);
;         const float ig = sigm(ai[tf][jj] + bi);
;         const float la = -8.0f * r * sp;
;         const float a = fexp(la);
;         const float bq = __builtin_amdgcn_sqrtf(fmaxf(1.f - a * a, 0.f)) * ig * XR[tt * 65 + j];
;         AA[(d * 64 + tt) * 64 + j] = a;
;         BQ[(d * 64 + tt) * 64 + j] = bq;
;       }
	v_mul_f32_e32 v34, v34, v56
	v_add_u32_e32 v43, 0, v35
	v_add_u32_e32 v35, s0, v35
	ds_write_b32 v35, v34
	v_fma_f32 v35, -v46, v46, 1.0
	ds_write_b32 v43, v55 offset:62720
	v_add_f32_e32 v34, 1.0, v38
	v_max_f32_e32 v35, 0, v35
	v_rcp_f32_e32 v34, v34
	v_sqrt_f32_e32 v35, v35
	ds_read_b32 v38, v54 offset:3900
	v_add_f32_e32 v39, v32, v39
	v_mul_f32_e32 v39, 0xbfb8aa3b, v39
	v_mul_f32_e32 v34, v34, v35
	v_exp_f32_e32 v39, v39
	s_waitcnt lgkmcnt(0)
	v_mul_f32_e32 v34, v34, v38
	v_add_f32_e32 v38, v33, v51
	v_mul_f32_e32 v38, 0xbfb8aa3b, v38
	v_exp_f32_e32 v38, v38
	v_or_b32_e32 v35, 0x1000, v64
	v_add_u32_e32 v47, 0, v35
	v_add_u32_e32 v35, s0, v35
	v_add_f32_e32 v38, 1.0, v38
	v_rcp_f32_e32 v38, v38
	ds_write_b32 v35, v34
	ds_write_b32 v47, v46 offset:62720
	v_add_f32_e32 v34, 1.0, v39
	v_mul_f32_e32 v38, 0xc1000000, v38
	v_mul_f32_e32 v38, v37, v38
	v_mul_f32_e32 v38, 0x3fb8aa3b, v38
	v_exp_f32_e32 v38, v38
	v_rcp_f32_e32 v34, v34
	ds_read_b32 v39, v54 offset:4160
	v_mfma_f32_16x16x32_bf16 v[42:45], v[58:61], v[12:15], 0
	v_fma_f32 v35, -v38, v38, 1.0
	v_max_f32_e32 v35, 0, v35
	v_sqrt_f32_e32 v35, v35
	v_mfma_f32_16x16x32_bf16 v[42:45], v[24:27], v[4:7], v[42:45]
	v_mul_f32_e32 v34, v34, v35
	s_waitcnt lgkmcnt(0)
	v_mul_f32_e32 v34, v34, v39
	v_add_f32_e32 v39, v33, v52
	v_mul_f32_e32 v39, 0xbfb8aa3b, v39
	v_exp_f32_e32 v39, v39
	v_or_b32_e32 v35, 0x1100, v64
	v_add_u32_e32 v50, 0, v35
	ds_write_b32 v50, v38 offset:62720
	v_add_f32_e32 v38, 1.0, v39
	v_rcp_f32_e32 v38, v38
	v_add_f32_e32 v39, v32, v40
	v_mul_f32_e32 v39, 0xbfb8aa3b, v39
	v_exp_f32_e32 v39, v39
	v_mul_f32_e32 v38, 0xc1000000, v38
	v_mul_f32_e32 v38, v37, v38
	v_mul_f32_e32 v38, 0x3fb8aa3b, v38
	v_exp_f32_e32 v38, v38
	v_add_u32_e32 v35, s0, v35
	ds_write_b32 v35, v34
	v_add_f32_e32 v34, 1.0, v39
	v_fma_f32 v35, -v38, v38, 1.0
	v_max_f32_e32 v35, 0, v35
	v_rcp_f32_e32 v34, v34
	v_sqrt_f32_e32 v35, v35
	ds_read_b32 v39, v54 offset:4420
	v_mfma_f32_16x16x32_bf16 v[46:49], v[58:61], v[8:11], 0
	v_mul_f32_e32 v34, v34, v35
	v_or_b32_e32 v35, 0x1200, v64
	s_waitcnt lgkmcnt(0)
	v_mul_f32_e32 v34, v34, v39
	v_add_f32_e32 v39, v33, v53
	v_mul_f32_e32 v39, 0xbfb8aa3b, v39
	v_exp_f32_e32 v39, v39
	v_add_u32_e32 v40, 0, v35
	ds_write_b32 v40, v38 offset:62720
	v_add_u32_e32 v35, s0, v35
	v_add_f32_e32 v38, 1.0, v39
	v_rcp_f32_e32 v38, v38
	v_add_f32_e32 v39, v32, v41
	v_mul_f32_e32 v39, 0xbfb8aa3b, v39
	v_exp_f32_e32 v39, v39
	v_mul_f32_e32 v38, 0xc1000000, v38
	v_mul_f32_e32 v38, v37, v38
	v_mul_f32_e32 v38, 0x3fb8aa3b, v38
	v_exp_f32_e32 v38, v38
	ds_write_b32 v35, v34
	v_add_f32_e32 v34, 1.0, v39
	v_rcp_f32_e32 v34, v34
	v_fma_f32 v35, -v38, v38, 1.0
	v_max_f32_e32 v35, 0, v35
	v_sqrt_f32_e32 v35, v35
	ds_read_b32 v39, v54 offset:4680
	v_mfma_f32_16x16x32_bf16 v[24:27], v[24:27], v[0:3], v[46:49]
	v_mul_f32_e32 v34, v34, v35
	v_or_b32_e32 v35, 0x1300, v64
	s_waitcnt lgkmcnt(0)
	v_mul_f32_e32 v34, v34, v39
	v_add_f32_e32 v39, v33, v42
	v_mul_f32_e32 v39, 0xbfb8aa3b, v39
	v_exp_f32_e32 v39, v39
	v_add_u32_e32 v40, 0, v35
	ds_write_b32 v40, v38 offset:62720
	v_add_f32_e32 v24, v32, v24
	v_add_f32_e32 v38, 1.0, v39
	v_rcp_f32_e32 v38, v38
	v_mul_f32_e32 v24, 0xbfb8aa3b, v24
	v_exp_f32_e32 v24, v24
	v_add_u32_e32 v35, s0, v35
	v_mul_f32_e32 v38, 0xc1000000, v38
	v_mul_f32_e32 v38, v37, v38
	v_mul_f32_e32 v38, 0x3fb8aa3b, v38
	v_exp_f32_e32 v38, v38
	ds_write_b32 v35, v34
	v_add_f32_e32 v24, 1.0, v24
	v_rcp_f32_e32 v24, v24
	v_fma_f32 v34, -v38, v38, 1.0
	v_max_f32_e32 v34, 0, v34
	v_sqrt_f32_e32 v34, v34
	ds_read_b32 v35, v54 offset:8060
	v_mfma_f32_16x16x32_bf16 v[12:15], v[20:23], v[12:15], 0
	v_add_f32_e32 v25, v32, v25
	v_mul_f32_e32 v24, v24, v34
	v_mul_f32_e32 v25, 0xbfb8aa3b, v25
	s_waitcnt lgkmcnt(0)
	v_mul_f32_e32 v24, v24, v35
	v_add_f32_e32 v35, v33, v43
	v_mul_f32_e32 v35, 0xbfb8aa3b, v35
	v_exp_f32_e32 v35, v35
	v_mfma_f32_16x16x32_bf16 v[8:11], v[20:23], v[8:11], 0
	v_add_f32_e32 v22, v33, v44
	v_mul_f32_e32 v22, 0xbfb8aa3b, v22
	v_add_f32_e32 v35, 1.0, v35
	v_rcp_f32_e32 v35, v35
	v_exp_f32_e32 v22, v22
	v_exp_f32_e32 v25, v25
	v_or_b32_e32 v34, 0x2000, v64
	v_mul_f32_e32 v35, 0xc1000000, v35
	v_mul_f32_e32 v35, v37, v35
	v_mul_f32_e32 v35, 0x3fb8aa3b, v35
	v_exp_f32_e32 v35, v35
	v_add_f32_e32 v22, 1.0, v22
	v_rcp_f32_e32 v22, v22
	v_mfma_f32_16x16x32_bf16 v[4:7], v[16:19], v[4:7], v[12:15]
	v_add_u32_e32 v39, 0, v34
	v_add_u32_e32 v34, s0, v34
	ds_write_b32 v34, v24
	v_add_f32_e32 v14, v33, v45
	v_mul_f32_e32 v14, 0xbfb8aa3b, v14
	v_add_f32_e32 v24, 1.0, v25
	v_fma_f32 v25, -v35, v35, 1.0
	v_exp_f32_e32 v14, v14
	ds_write_b32 v39, v38 offset:62720
	v_max_f32_e32 v25, 0, v25
	v_or_b32_e32 v21, 0x2100, v64
	v_mul_f32_e32 v22, 0xc1000000, v22
	v_rcp_f32_e32 v24, v24
	v_sqrt_f32_e32 v25, v25
	ds_read_b32 v34, v54 offset:8320
	v_add_u32_e32 v23, 0, v21
	v_mul_f32_e32 v22, v37, v22
	ds_write_b32 v23, v35 offset:62720
	v_add_f32_e32 v23, v32, v26
	v_mul_f32_e32 v22, 0x3fb8aa3b, v22
	v_mul_f32_e32 v23, 0xbfb8aa3b, v23
	v_exp_f32_e32 v22, v22
	v_add_f32_e32 v14, 1.0, v14
	v_exp_f32_e32 v23, v23
	v_rcp_f32_e32 v14, v14
	v_mul_f32_e32 v20, v24, v25
	v_add_f32_e32 v4, v33, v4
	s_waitcnt lgkmcnt(1)
	v_mul_f32_e32 v20, v20, v34
	v_add_u32_e32 v21, s0, v21
	v_mul_f32_e32 v4, 0xbfb8aa3b, v4
	ds_write_b32 v21, v20
	v_fma_f32 v21, -v22, v22, 1.0
	v_exp_f32_e32 v4, v4
	v_add_f32_e32 v20, 1.0, v23
	v_max_f32_e32 v21, 0, v21
	v_or_b32_e32 v13, 0x2200, v64
	v_mul_f32_e32 v14, 0xc1000000, v14
	v_rcp_f32_e32 v20, v20
	v_sqrt_f32_e32 v21, v21
	ds_read_b32 v23, v54 offset:8580
	v_add_u32_e32 v15, 0, v13
	v_mul_f32_e32 v14, v37, v14
	ds_write_b32 v15, v22 offset:62720
	v_add_f32_e32 v15, v32, v27
	v_mul_f32_e32 v14, 0x3fb8aa3b, v14
	v_mul_f32_e32 v15, 0xbfb8aa3b, v15
	v_exp_f32_e32 v14, v14
	v_add_f32_e32 v4, 1.0, v4
	v_exp_f32_e32 v15, v15
	v_rcp_f32_e32 v4, v4
	v_mul_f32_e32 v12, v20, v21
	s_waitcnt lgkmcnt(1)
	v_mul_f32_e32 v12, v12, v23
	v_add_u32_e32 v13, s0, v13
	v_mfma_f32_16x16x32_bf16 v[0:3], v[16:19], v[0:3], v[8:11]
	v_add_f32_e32 v5, v33, v5
	ds_write_b32 v13, v12
	v_fma_f32 v13, -v14, v14, 1.0
	v_mul_f32_e32 v5, 0xbfb8aa3b, v5
	v_add_f32_e32 v12, 1.0, v15
	v_max_f32_e32 v13, 0, v13
	v_mul_f32_e32 v4, 0xc1000000, v4
	v_exp_f32_e32 v5, v5
	v_rcp_f32_e32 v12, v12
	v_sqrt_f32_e32 v13, v13
	ds_read_b32 v15, v54 offset:8840
	v_mul_f32_e32 v4, v37, v4
	v_add_f32_e32 v0, v32, v0
	v_mul_f32_e32 v4, 0x3fb8aa3b, v4
	v_mul_f32_e32 v0, 0xbfb8aa3b, v0
	v_exp_f32_e32 v4, v4
	v_exp_f32_e32 v0, v0
	v_add_f32_e32 v5, 1.0, v5
	v_mul_f32_e32 v8, v12, v13
	v_or_b32_e32 v9, 0x2300, v64
	v_rcp_f32_e32 v5, v5
	s_waitcnt lgkmcnt(0)
	v_mul_f32_e32 v8, v8, v15
	v_add_u32_e32 v10, 0, v9
	v_add_u32_e32 v9, s0, v9
	ds_write_b32 v9, v8
	v_fma_f32 v8, -v4, v4, 1.0
	ds_write_b32 v10, v14 offset:62720
	v_add_f32_e32 v0, 1.0, v0
	v_max_f32_e32 v8, 0, v8
	v_rcp_f32_e32 v0, v0
	v_sqrt_f32_e32 v8, v8
	ds_read_b32 v9, v54 offset:12220
	v_mul_f32_e32 v5, 0xc1000000, v5
	v_add_f32_e32 v1, v32, v1
	v_mul_f32_e32 v5, v37, v5
	v_mul_f32_e32 v1, 0xbfb8aa3b, v1
	v_mul_f32_e32 v5, 0x3fb8aa3b, v5
	v_exp_f32_e32 v1, v1
	v_exp_f32_e32 v5, v5
	v_mul_f32_e32 v0, v0, v8
	v_or_b32_e32 v8, 0x3000, v64
	s_waitcnt lgkmcnt(0)
	v_mul_f32_e32 v0, v0, v9
	v_add_u32_e32 v9, 0, v8
	ds_write_b32 v9, v4 offset:62720
	v_add_u32_e32 v4, s0, v8
	ds_write_b32 v4, v0
	v_add_f32_e32 v0, 1.0, v1
	v_fma_f32 v1, -v5, v5, 1.0
	v_max_f32_e32 v1, 0, v1
	v_rcp_f32_e32 v0, v0
	v_sqrt_f32_e32 v1, v1
	ds_read_b32 v4, v54 offset:12480
	v_add_f32_e32 v2, v32, v2
	v_mul_f32_e32 v2, 0xbfb8aa3b, v2
	v_mul_f32_e32 v0, v0, v1
	v_exp_f32_e32 v2, v2
	s_waitcnt lgkmcnt(0)
	v_mul_f32_e32 v0, v0, v4
	v_add_f32_e32 v4, v33, v6
	v_mul_f32_e32 v4, 0xbfb8aa3b, v4
	v_exp_f32_e32 v4, v4
	v_or_b32_e32 v1, 0x3100, v64
	v_add_u32_e32 v6, 0, v1
	v_add_u32_e32 v1, s0, v1
	v_add_f32_e32 v4, 1.0, v4
	v_rcp_f32_e32 v4, v4
	ds_write_b32 v1, v0
	ds_write_b32 v6, v5 offset:62720
	v_add_f32_e32 v0, 1.0, v2
	v_mul_f32_e32 v4, 0xc1000000, v4
	v_mul_f32_e32 v4, v37, v4
	v_mul_f32_e32 v4, 0x3fb8aa3b, v4
	v_exp_f32_e32 v4, v4
	v_rcp_f32_e32 v0, v0
	ds_read_b32 v2, v54 offset:12740
	v_add_f32_e32 v3, v32, v3
	v_fma_f32 v1, -v4, v4, 1.0
	v_max_f32_e32 v1, 0, v1
	v_sqrt_f32_e32 v1, v1
	v_mul_f32_e32 v3, 0xbfb8aa3b, v3
	v_exp_f32_e32 v3, v3
	v_lshlrev_b32_e32 v15, 4, v36
	v_mul_f32_e32 v0, v0, v1
	s_waitcnt lgkmcnt(0)
	v_mul_f32_e32 v0, v0, v2
	v_add_f32_e32 v2, v33, v7
	v_mul_f32_e32 v2, 0xbfb8aa3b, v2
	v_exp_f32_e32 v2, v2
	v_or_b32_e32 v1, 0x3200, v64
	v_add_u32_e32 v5, 0, v1
	v_add_u32_e32 v1, s0, v1
	v_add_f32_e32 v2, 1.0, v2
	v_rcp_f32_e32 v2, v2
	ds_write_b32 v1, v0
	ds_write_b32 v5, v4 offset:62720
	v_add_f32_e32 v0, 1.0, v3
	v_mul_f32_e32 v2, 0xc1000000, v2
	v_mul_f32_e32 v2, v37, v2
	v_mul_f32_e32 v2, 0x3fb8aa3b, v2
	v_exp_f32_e32 v2, v2
	v_rcp_f32_e32 v0, v0
	ds_read_b32 v3, v54 offset:13000
	v_and_b32_e32 v18, 1, v28
	v_fma_f32 v1, -v2, v2, 1.0
	v_max_f32_e32 v1, 0, v1
	v_sqrt_f32_e32 v1, v1
	v_or_b32_e32 v4, 2, v15
	v_or_b32_e32 v6, 3, v15
	v_cmp_eq_u32_e32 vcc, 0, v18
	v_mul_f32_e32 v0, v0, v1
	v_or_b32_e32 v1, 0x3300, v64
	s_waitcnt lgkmcnt(0)
	v_mul_f32_e32 v0, v0, v3
	v_add_u32_e32 v3, 0, v1
	ds_write_b32 v3, v2 offset:62720
	v_add_u32_e32 v1, s0, v1
	v_or_b32_e32 v2, 1, v15
	ds_write_b32 v1, v0
	v_sub_u32_e32 v0, 63, v15
	v_sub_u32_e32 v3, 63, v2
	v_sub_u32_e32 v5, 63, v4
	v_sub_u32_e32 v7, 63, v6
	v_cndmask_b32_e32 v0, v0, v15, vcc
	v_cndmask_b32_e32 v2, v3, v2, vcc
	v_cndmask_b32_e32 v4, v5, v4, vcc
	v_cndmask_b32_e32 v6, v7, v6, vcc
	v_lshl_or_b32 v19, v18, 12, v31
	v_lshlrev_b32_e32 v0, 6, v0
	v_lshlrev_b32_e32 v2, 6, v2
	v_lshlrev_b32_e32 v4, 6, v4
	v_lshlrev_b32_e32 v6, 6, v6
	v_add_lshl_u32 v0, v0, v19, 2
	v_add_lshl_u32 v2, v2, v19, 2
	v_add_lshl_u32 v4, v4, v19, 2
	v_add_lshl_u32 v6, v6, v19, 2
	v_add_u32_e32 v1, 0, v0
	v_add_u32_e32 v0, s0, v0
	v_add_u32_e32 v3, 0, v2
	v_add_u32_e32 v2, s0, v2
	v_add_u32_e32 v5, 0, v4
	v_add_u32_e32 v7, 0, v6
	s_waitcnt lgkmcnt(0)
	s_barrier
	v_add_u32_e32 v4, s0, v4
	v_add_u32_e32 v6, s0, v6
	ds_read_b32 v1, v1 offset:62720
	ds_read_b32 v8, v0
	ds_read_b32 v3, v3 offset:62720
	ds_read_b32 v9, v2
	ds_read_b32 v0, v5 offset:62720
	ds_read_b32 v5, v4
	ds_read_b32 v2, v7 offset:62720
	ds_read_b32 v7, v6
	s_waitcnt lgkmcnt(6)
	v_fmac_f32_e32 v8, 0, v1
	v_or_b32_e32 v6, 5, v15
	s_waitcnt lgkmcnt(4)
	v_fmac_f32_e32 v9, v8, v3
	v_sub_u32_e32 v8, 63, v6
	v_cndmask_b32_e32 v6, v8, v6, vcc
	v_lshlrev_b32_e32 v6, 6, v6
	v_add_lshl_u32 v6, v6, v19, 2
	s_waitcnt lgkmcnt(2)
	v_fmac_f32_e32 v5, v9, v0
	v_add_u32_e32 v8, 0, v6
	v_add_u32_e32 v9, s0, v6
	v_or_b32_e32 v6, 6, v15
	v_sub_u32_e32 v10, 63, v6
	v_cndmask_b32_e32 v6, v10, v6, vcc
	v_lshlrev_b32_e32 v6, 6, v6
	v_add_lshl_u32 v6, v6, v19, 2
	v_mul_f32_e32 v4, v1, v3
	v_or_b32_e32 v1, 4, v15
	v_add_u32_e32 v10, 0, v6
	v_add_u32_e32 v11, s0, v6
	v_or_b32_e32 v6, 7, v15
	v_sub_u32_e32 v3, 63, v1
	v_sub_u32_e32 v12, 63, v6
	v_cndmask_b32_e32 v1, v3, v1, vcc
	v_cndmask_b32_e32 v6, v12, v6, vcc
	v_lshlrev_b32_e32 v1, 6, v1
	v_lshlrev_b32_e32 v6, 6, v6
	v_add_lshl_u32 v1, v1, v19, 2
	v_add_lshl_u32 v6, v6, v19, 2
	v_add_u32_e32 v3, 0, v1
	v_add_u32_e32 v1, s0, v1
	v_add_u32_e32 v12, 0, v6
	v_add_u32_e32 v13, s0, v6
	ds_read_b32 v6, v3 offset:62720
	ds_read_b32 v1, v1
	ds_read_b32 v8, v8 offset:62720
	ds_read_b32 v3, v9
	ds_read_b32 v10, v10 offset:62720
	ds_read_b32 v9, v11
	ds_read_b32 v12, v12 offset:62720
	ds_read_b32 v16, v13
	s_waitcnt lgkmcnt(8)
	v_fmac_f32_e32 v7, v5, v2
	v_or_b32_e32 v5, 9, v15
	s_waitcnt lgkmcnt(6)
	v_fmac_f32_e32 v1, v7, v6
	v_sub_u32_e32 v7, 63, v5
	v_cndmask_b32_e32 v5, v7, v5, vcc
	s_waitcnt lgkmcnt(4)
	v_fmac_f32_e32 v3, v1, v8
	v_lshlrev_b32_e32 v5, 6, v5
	s_waitcnt lgkmcnt(2)
	v_fmac_f32_e32 v9, v3, v10
	v_add_lshl_u32 v5, v5, v19, 2
	s_waitcnt lgkmcnt(0)
	v_fmac_f32_e32 v16, v9, v12
	v_add_u32_e32 v7, 0, v5
	v_add_u32_e32 v9, s0, v5
	v_or_b32_e32 v5, 10, v15
	v_sub_u32_e32 v11, 63, v5
	v_cndmask_b32_e32 v5, v11, v5, vcc
	v_lshlrev_b32_e32 v5, 6, v5
	v_or_b32_e32 v1, 8, v15
	v_add_lshl_u32 v5, v5, v19, 2
	v_sub_u32_e32 v3, 63, v1
	v_add_u32_e32 v11, 0, v5
	v_add_u32_e32 v13, s0, v5
	v_or_b32_e32 v5, 11, v15
	v_cndmask_b32_e32 v1, v3, v1, vcc
	v_sub_u32_e32 v14, 63, v5
	v_lshlrev_b32_e32 v1, 6, v1
	v_cndmask_b32_e32 v5, v14, v5, vcc
	v_add_lshl_u32 v1, v1, v19, 2
	v_lshlrev_b32_e32 v5, 6, v5
	v_add_u32_e32 v3, 0, v1
	v_add_u32_e32 v1, s0, v1
	v_add_lshl_u32 v5, v5, v19, 2
	v_add_u32_e32 v17, 0, v5
	v_add_u32_e32 v20, s0, v5
	ds_read_b32 v14, v3 offset:62720
	ds_read_b32 v5, v1
	ds_read_b32 v1, v7 offset:62720
	ds_read_b32 v3, v9
	ds_read_b32 v7, v11 offset:62720
	ds_read_b32 v9, v13
	ds_read_b32 v11, v17 offset:62720
	ds_read_b32 v13, v20
	s_waitcnt lgkmcnt(6)
	v_fmac_f32_e32 v5, v16, v14
	v_mul_f32_e32 v16, v4, v0
	v_mul_f32_e32 v16, v16, v2
	s_waitcnt lgkmcnt(4)
	v_pk_fma_f32 v[2:3], v[4:5], v[0:1], v[2:3]
	v_or_b32_e32 v0, 12, v15
	v_mov_b32_e32 v17, v3
	s_waitcnt lgkmcnt(3)
	v_pk_mul_f32 v[2:3], v[16:17], v[6:7]
	s_waitcnt lgkmcnt(2)
	v_pk_fma_f32 v[4:5], v[16:17], v[6:7], v[8:9]
	v_pk_mul_f32 v[2:3], v[2:3], v[8:9]
	v_or_b32_e32 v8, 13, v15
	v_sub_u32_e32 v9, 63, v8
	v_cndmask_b32_e32 v8, v9, v8, vcc
	v_or_b32_e32 v9, 14, v15
	v_sub_u32_e32 v17, 63, v9
	v_cndmask_b32_e32 v9, v17, v9, vcc
	v_lshlrev_b32_e32 v9, 6, v9
	v_add_lshl_u32 v9, v9, v19, 2
	v_sub_u32_e32 v6, 63, v0
	v_add_u32_e32 v20, 0, v9
	v_add_u32_e32 v22, s0, v9
	v_or_b32_e32 v9, 15, v15
	v_cndmask_b32_e32 v0, v6, v0, vcc
	v_sub_u32_e32 v15, 63, v9
	v_lshlrev_b32_e32 v0, 6, v0
	v_cndmask_b32_e32 v9, v15, v9, vcc
	v_add_lshl_u32 v0, v0, v19, 2
	v_lshlrev_b32_e32 v8, 6, v8
	v_lshlrev_b32_e32 v9, 6, v9
	v_mov_b32_e32 v4, v2
	v_add_u32_e32 v6, 0, v0
	v_add_u32_e32 v0, s0, v0
	v_add_lshl_u32 v8, v8, v19, 2
	v_add_lshl_u32 v9, v9, v19, 2
	s_waitcnt lgkmcnt(1)
	v_pk_mul_f32 v[2:3], v[2:3], v[10:11]
	v_add_u32_e32 v16, 0, v8
	v_add_u32_e32 v8, s0, v8
	v_add_u32_e32 v24, 0, v9
	v_add_u32_e32 v26, s0, v9
	ds_read_b32 v15, v6 offset:62720
	ds_read_b32 v9, v0
	ds_read_b32 v17, v16 offset:62720
	ds_read_b32 v19, v8
	ds_read_b32 v21, v20 offset:62720
	ds_read_b32 v23, v22
	ds_read_b32 v25, v24 offset:62720
	ds_read_b32 v27, v26
	v_and_b32_e32 v0, 0x1fffff80, v29
	v_lshlrev_b32_e32 v6, 6, v18
	s_waitcnt lgkmcnt(8)
	v_pk_mul_f32 v[2:3], v[2:3], v[12:13]
	v_pk_fma_f32 v[4:5], v[4:5], v[10:11], v[12:13]
	v_or3_b32 v0, v6, v0, v31
	v_mov_b32_e32 v3, v5
	v_lshl_add_u32 v6, v0, 3, 0
	s_waitcnt lgkmcnt(7)
	v_pk_mul_f32 v[4:5], v[2:3], v[14:15]
	v_mov_b32_e32 v0, v1
	v_mov_b32_e32 v8, v1
	v_pk_mul_f32 v[0:1], v[4:5], v[0:1]
	s_waitcnt lgkmcnt(6)
	v_pk_fma_f32 v[2:3], v[2:3], v[14:15], v[8:9]
	v_mov_b32_e32 v4, v7
	v_mov_b32_e32 v2, v0
	v_mov_b32_e32 v16, v7
	v_pk_mul_f32 v[0:1], v[0:1], v[4:5]
	v_mov_b32_e32 v4, v11
	v_mov_b32_e32 v18, v11
	v_pk_mul_f32 v[0:1], v[0:1], v[4:5]
	s_waitcnt lgkmcnt(4)
	v_pk_fma_f32 v[2:3], v[2:3], v[16:17], v[18:19]
	v_mov_b32_e32 v20, v15
	v_mov_b32_e32 v1, v3
	s_waitcnt lgkmcnt(3)
	v_pk_mul_f32 v[2:3], v[0:1], v[20:21]
	v_mov_b32_e32 v4, v17
	v_mov_b32_e32 v22, v17
	v_pk_mul_f32 v[2:3], v[2:3], v[4:5]
	s_waitcnt lgkmcnt(2)
	v_pk_fma_f32 v[0:1], v[0:1], v[20:21], v[22:23]
	v_mov_b32_e32 v4, v21
	v_mov_b32_e32 v0, v2
	v_mov_b32_e32 v24, v21
	v_pk_mul_f32 v[2:3], v[2:3], v[4:5]
	s_waitcnt lgkmcnt(1)
	v_mov_b32_e32 v4, v25
	v_mov_b32_e32 v26, v25
	v_pk_mul_f32 v[2:3], v[2:3], v[4:5]
	s_waitcnt lgkmcnt(0)
	v_pk_fma_f32 v[0:1], v[0:1], v[24:25], v[26:27]
	v_cmp_gt_u32_e32 vcc, s91, v29
	v_mov_b32_e32 v3, v1
	ds_write_b64 v6, v[2:3]
	s_waitcnt lgkmcnt(0)
	s_barrier
	s_and_saveexec_b64 s[0:1], vcc
	s_cbranch_execz .LBB0_329
	v_lshlrev_b32_e32 v0, 3, v29
	v_add_u32_e32 v4, 0, v0
	ds_read2st64_b64 v[0:3], v4 offset1:2
	ds_read2st64_b64 v[4:7], v4 offset0:4 offset1:6
	s_mul_i32 s3, s3, 36
	s_add_i32 s3, s3, s2
	s_lshl_b32 s2, s3, 9
	s_waitcnt lgkmcnt(1)
	v_fma_f32 v1, 0, v0, v1
	v_fmac_f32_e32 v3, v1, v2
	v_lshlrev_b32_e32 v8, 8, v28
	v_mul_f32_e32 v0, v0, v2
	s_waitcnt lgkmcnt(0)
	v_fma_f32 v1, v3, v4, v5
	v_mov_b32_e32 v5, v6
	v_or3_b32 v192, v8, s2, v30
	v_readlane_b32 s2, v251, 56
	v_pk_mul_f32 v[8:9], v[0:1], v[4:5]
	v_readlane_b32 s3, v251, 57
	v_pk_mul_f32 v[8:9], v[8:9], v[6:7]
	v_pk_fma_f32 v[0:1], v[0:1], v[4:5], v[6:7]
	v_lshl_add_u64 v[2:3], v[192:193], 3, s[2:3]
	v_mov_b32_e32 v9, v1
	global_store_dwordx2 v[2:3], v[8:9], off

.LBB0_639:
	s_cmp_ge_i32 s13, s30
	s_mov_b64 s[0:1], -1
	s_cbranch_scc0 .LBB0_714
	v_readlane_b32 s0, v254, 23
	s_cmp_ge_i32 s13, s0
	s_mov_b64 s[0:1], -1
	s_cbranch_scc0 .LBB0_708
	v_readlane_b32 s0, v254, 23
	s_sub_i32 s0, s13, s0
	v_readlane_b32 s1, v254, 14
	s_mul_hi_u32 s1, s0, s1
	v_readlane_b32 s5, v254, 11
	s_mul_i32 s2, s1, s5
	s_sub_i32 s2, s0, s2
	s_add_i32 s3, s1, 1
	s_sub_i32 s4, s2, s5
	s_cmp_ge_u32 s2, s5
	s_cselect_b32 s1, s3, s1
	s_cselect_b32 s2, s4, s2
	s_add_i32 s3, s1, 1
	s_cmp_ge_u32 s2, s5
	s_cselect_b32 s96, s3, s1
	s_mul_i32 s1, s96, s5
	s_sub_i32 s0, s0, s1
	v_readlane_b32 s1, v254, 22
	s_add_i32 s0, s0, s1
	s_cmp_lt_u32 s0, 4
	s_cselect_b64 s[2:3], -1, 0
	s_lshl_b32 s4, s0, 6
	s_add_i32 s5, s4, 0xffffff00
	s_lshl_b32 s1, s96, 8
	s_add_i32 s6, s1, 0x4000
	s_lshl_b32 s7, s96, 11
	s_movk_i32 s8, 0x100
	s_movk_i32 s9, 0x800
	s_mov_b32 s10, 0
	s_cmp_lt_u32 s0, 4
	s_cselect_b32 s44, s4, s5
	s_cselect_b32 s45, s8, s9
	s_cselect_b32 s46, s6, s7
	s_cselect_b32 s47, s9, s10
	v_readfirstlane_b32 s48, v195
	v_and_b32_e32 v0, 63, v195
	v_readlane_b32 s52, v252, 3
	v_readlane_b32 s53, v252, 4
	v_readlane_b32 s54, v254, 7
	v_readlane_b32 s55, v254, 8
	v_readlane_b32 s56, v254, 9
	v_readlane_b32 s57, v254, 10
	v_readlane_b32 s58, v251, 31
	v_readlane_b32 s59, v251, 32
	s_lshr_b32 s48, s48, 6
	s_lshl_b32 s49, s48, 3
	s_add_i32 s49, s49, s44
	s_mul_i32 s1, s96, 0x1200
	s_add_i32 s4, s47, s49
	s_lshl_b32 s4, s4, 1
	s_add_i32 s1, s1, s4
	s_add_u32 s52, s52, s1
	s_addc_u32 s53, s53, 0
	s_add_i32 s1, s46, s49
	s_lshl_b32 s4, s1, 11
	s_add_u32 s58, s58, s4
	s_addc_u32 s59, s59, 0
	s_mul_i32 s50, s1, 0x1a00
	s_add_i32 s4, s49, -1
	s_max_i32 s4, s4, 0
	s_add_i32 s4, s4, s46
	s_mul_i32 s51, s4, 0x1a00
	s_add_i32 s4, s49, 8
	s_add_i32 s5, s45, -1
	s_min_i32 s4, s4, s5
	s_add_i32 s4, s4, s46
	s_mul_i32 s5, s4, 0x1a00
	v_lshlrev_b32_e32 v9, 3, v0
	v_lshlrev_b32_e32 v6, 4, v0
	v_add_u32_e32 v7, 0x1800, v6
	v_mov_b32_e32 v8, v9
	s_mov_b32 s6, 0x24000
	v_mul_lo_u32 v2, v0, s6
	v_add_u32_e32 v3, 0x9000, v2
	v_add_u32_e32 v4, 0x12000, v2
	v_add_u32_e32 v5, 0x1b000, v2
	v_add_u32_e32 v1, s50, v9
	v_add_u32_e32 v82, s51, v9
	global_load_dwordx2 v[10:11], v82, s[88:89]
	global_load_dwordx2 v[12:13], v1, s[88:89]
	v_add_u32_e32 v1, 0x1a00, v1
	global_load_dwordx2 v[14:15], v1, s[88:89]
	v_add_u32_e32 v1, 0x1a00, v1
	global_load_dwordx2 v[16:17], v1, s[88:89]
	v_add_u32_e32 v1, 0x1a00, v1
	global_load_dwordx2 v[18:19], v1, s[88:89]
	v_add_u32_e32 v1, 0x1a00, v1
	global_load_dwordx2 v[20:21], v1, s[88:89]
	v_add_u32_e32 v1, 0x1a00, v1
	global_load_dwordx2 v[22:23], v1, s[88:89]
	v_add_u32_e32 v1, 0x1a00, v1
	global_load_dwordx2 v[24:25], v1, s[88:89]
	v_add_u32_e32 v1, 0x1a00, v1
	global_load_dwordx2 v[26:27], v1, s[88:89]
	v_add_u32_e32 v82, s5, v9
	global_load_dwordx2 v[28:29], v82, s[88:89]
	global_load_dwordx4 v[46:49], v6, s[54:55]
	global_load_dwordx4 v[50:53], v6, s[54:55] offset:3072
	global_load_dwordx4 v[54:57], v7, s[54:55]
	global_load_dwordx4 v[58:61], v6, s[56:57]
	global_load_dwordx4 v[30:33], v2, s[52:53]
	global_load_dwordx4 v[34:37], v3, s[52:53]
	global_load_dwordx4 v[38:41], v4, s[52:53]
	global_load_dwordx4 v[42:45], v5, s[52:53]
	s_cmp_ge_i32 s49, 1
	s_cselect_b64 s[60:61], -1, 0
	s_add_i32 s4, s49, 8
	s_cmp_lt_i32 s4, s45
	s_cselect_b64 s[6:7], -1, 0
	s_waitcnt vmcnt(0)
	v_cndmask_b32_e64 v62, 0, v46, s[60:61]
	v_cndmask_b32_e64 v66, 0, v54, s[6:7]
	v_cndmask_b32_e64 v63, 0, v47, s[60:61]
	v_cndmask_b32_e64 v67, 0, v55, s[6:7]
	v_cndmask_b32_e64 v64, 0, v48, s[60:61]
	v_cndmask_b32_e64 v68, 0, v56, s[6:7]
	v_cndmask_b32_e64 v65, 0, v49, s[60:61]
	v_cndmask_b32_e64 v69, 0, v57, s[6:7]
	v_lshlrev_b32_e32 v70, 16, v10
	v_and_b32_e32 v71, 0xffff0000, v10
	v_lshlrev_b32_e32 v72, 16, v11
	v_and_b32_e32 v73, 0xffff0000, v11
	v_lshlrev_b32_e32 v74, 16, v12
	v_and_b32_e32 v75, 0xffff0000, v12
	v_lshlrev_b32_e32 v76, 16, v13
	v_and_b32_e32 v77, 0xffff0000, v13
	v_lshlrev_b32_e32 v78, 16, v14
	v_and_b32_e32 v79, 0xffff0000, v14
	v_lshlrev_b32_e32 v80, 16, v15
	v_and_b32_e32 v81, 0xffff0000, v15
	v_mul_f32_e32 v154, v62, v70
	v_mul_f32_e32 v155, v63, v71
	v_mul_f32_e32 v156, v64, v72
	v_mul_f32_e32 v157, v65, v73
	v_fmac_f32_e32 v154, v50, v74
	v_fmac_f32_e32 v155, v51, v75
	v_fmac_f32_e32 v156, v52, v76
	v_fmac_f32_e32 v157, v53, v77
	v_fmac_f32_e32 v154, v54, v78
	v_fmac_f32_e32 v155, v55, v79
	v_fmac_f32_e32 v156, v56, v80
	v_fmac_f32_e32 v157, v57, v81
	v_lshlrev_b32_e32 v158, 16, v30
	v_lshlrev_b32_e32 v159, 16, v34
	v_lshlrev_b32_e32 v160, 16, v38
	v_lshlrev_b32_e32 v161, 16, v42
	v_mul_f32_e32 v162, v154, v158
	v_mul_f32_e32 v163, v155, v159
	v_mul_f32_e32 v164, v156, v160
	v_mul_f32_e32 v165, v157, v161
	v_mul_f32_e32 v178, v162, v162
	v_fmac_f32_e32 v178, v163, v163
	v_fmac_f32_e32 v178, v164, v164
	v_fmac_f32_e32 v178, v165, v165
	v_lshlrev_b32_e32 v70, 16, v16
	v_and_b32_e32 v71, 0xffff0000, v16
	v_lshlrev_b32_e32 v72, 16, v17
	v_and_b32_e32 v73, 0xffff0000, v17
	v_mul_f32_e32 v154, v46, v74
	v_mul_f32_e32 v155, v47, v75
	v_mul_f32_e32 v156, v48, v76
	v_mul_f32_e32 v157, v49, v77
	v_fmac_f32_e32 v154, v50, v78
	v_fmac_f32_e32 v155, v51, v79
	v_fmac_f32_e32 v156, v52, v80
	v_fmac_f32_e32 v157, v53, v81
	v_fmac_f32_e32 v154, v54, v70
	v_fmac_f32_e32 v155, v55, v71
	v_fmac_f32_e32 v156, v56, v72
	v_fmac_f32_e32 v157, v57, v73
	v_and_b32_e32 v158, 0xffff0000, v30
	v_and_b32_e32 v159, 0xffff0000, v34
	v_and_b32_e32 v160, 0xffff0000, v38
	v_and_b32_e32 v161, 0xffff0000, v42
	v_mul_f32_e32 v166, v154, v158
	v_mul_f32_e32 v167, v155, v159
	v_mul_f32_e32 v168, v156, v160
	v_mul_f32_e32 v169, v157, v161
	v_mul_f32_e32 v179, v166, v166
	v_fmac_f32_e32 v179, v167, v167
	v_fmac_f32_e32 v179, v168, v168
	v_fmac_f32_e32 v179, v169, v169
	v_lshlrev_b32_e32 v74, 16, v18
	v_and_b32_e32 v75, 0xffff0000, v18
	v_lshlrev_b32_e32 v76, 16, v19
	v_and_b32_e32 v77, 0xffff0000, v19
	v_mul_f32_e32 v154, v46, v78
	v_mul_f32_e32 v155, v47, v79
	v_mul_f32_e32 v156, v48, v80
	v_mul_f32_e32 v157, v49, v81
	v_fmac_f32_e32 v154, v50, v70
	v_fmac_f32_e32 v155, v51, v71
	v_fmac_f32_e32 v156, v52, v72
	v_fmac_f32_e32 v157, v53, v73
	v_fmac_f32_e32 v154, v54, v74
	v_fmac_f32_e32 v155, v55, v75
	v_fmac_f32_e32 v156, v56, v76
	v_fmac_f32_e32 v157, v57, v77
	v_lshlrev_b32_e32 v158, 16, v31
	v_lshlrev_b32_e32 v159, 16, v35
	v_lshlrev_b32_e32 v160, 16, v39
	v_lshlrev_b32_e32 v161, 16, v43
	v_mul_f32_e32 v170, v154, v158
	v_mul_f32_e32 v171, v155, v159
	v_mul_f32_e32 v172, v156, v160
	v_mul_f32_e32 v173, v157, v161
	v_mul_f32_e32 v180, v170, v170
	v_fmac_f32_e32 v180, v171, v171
	v_fmac_f32_e32 v180, v172, v172
	v_fmac_f32_e32 v180, v173, v173
	v_lshlrev_b32_e32 v78, 16, v20
	v_and_b32_e32 v79, 0xffff0000, v20
	v_lshlrev_b32_e32 v80, 16, v21
	v_and_b32_e32 v81, 0xffff0000, v21
	v_mul_f32_e32 v154, v46, v70
	v_mul_f32_e32 v155, v47, v71
	v_mul_f32_e32 v156, v48, v72
	v_mul_f32_e32 v157, v49, v73
	v_fmac_f32_e32 v154, v50, v74
	v_fmac_f32_e32 v155, v51, v75
	v_fmac_f32_e32 v156, v52, v76
	v_fmac_f32_e32 v157, v53, v77
	v_fmac_f32_e32 v154, v54, v78
	v_fmac_f32_e32 v155, v55, v79
	v_fmac_f32_e32 v156, v56, v80
	v_fmac_f32_e32 v157, v57, v81
	v_and_b32_e32 v158, 0xffff0000, v31
	v_and_b32_e32 v159, 0xffff0000, v35
	v_and_b32_e32 v160, 0xffff0000, v39
	v_and_b32_e32 v161, 0xffff0000, v43
	v_mul_f32_e32 v174, v154, v158
	v_mul_f32_e32 v175, v155, v159
	v_mul_f32_e32 v176, v156, v160
	v_mul_f32_e32 v177, v157, v161
	v_mul_f32_e32 v181, v174, v174
	v_fmac_f32_e32 v181, v175, v175
	v_fmac_f32_e32 v181, v176, v176
	v_fmac_f32_e32 v181, v177, v177
	s_nop 1
	v_add_f32_dpp v178, v178, v178 quad_perm:[1,0,3,2] row_mask:0xf bank_mask:0xf
	v_add_f32_dpp v179, v179, v179 quad_perm:[1,0,3,2] row_mask:0xf bank_mask:0xf
	v_add_f32_dpp v180, v180, v180 quad_perm:[1,0,3,2] row_mask:0xf bank_mask:0xf
	v_add_f32_dpp v181, v181, v181 quad_perm:[1,0,3,2] row_mask:0xf bank_mask:0xf
	v_add_f32_dpp v178, v178, v178 quad_perm:[2,3,0,1] row_mask:0xf bank_mask:0xf
	v_add_f32_dpp v179, v179, v179 quad_perm:[2,3,0,1] row_mask:0xf bank_mask:0xf
	v_add_f32_dpp v180, v180, v180 quad_perm:[2,3,0,1] row_mask:0xf bank_mask:0xf
	v_add_f32_dpp v181, v181, v181 quad_perm:[2,3,0,1] row_mask:0xf bank_mask:0xf
	v_add_f32_dpp v178, v178, v178 row_half_mirror row_mask:0xf bank_mask:0xf
	v_add_f32_dpp v179, v179, v179 row_half_mirror row_mask:0xf bank_mask:0xf
	v_add_f32_dpp v180, v180, v180 row_half_mirror row_mask:0xf bank_mask:0xf
	v_add_f32_dpp v181, v181, v181 row_half_mirror row_mask:0xf bank_mask:0xf
	v_add_f32_dpp v178, v178, v178 row_mirror row_mask:0xf bank_mask:0xf
	v_add_f32_dpp v179, v179, v179 row_mirror row_mask:0xf bank_mask:0xf
	v_add_f32_dpp v180, v180, v180 row_mirror row_mask:0xf bank_mask:0xf
	v_add_f32_dpp v181, v181, v181 row_mirror row_mask:0xf bank_mask:0xf
	v_fmamk_f32 v186, v178, 0x3c800000, v194
	v_fmamk_f32 v187, v179, 0x3c800000, v194
	v_fmamk_f32 v188, v180, 0x3c800000, v194
	v_fmamk_f32 v189, v181, 0x3c800000, v194
	v_rsq_f32_e32 v186, v186
	v_rsq_f32_e32 v187, v187
	v_rsq_f32_e32 v188, v188
	v_rsq_f32_e32 v189, v189
	s_nop 0
	v_mul_f32_e32 v162, v162, v186
	v_mul_f32_e32 v163, v163, v186
	v_mul_f32_e32 v164, v164, v186
	v_mul_f32_e32 v165, v165, v186
	v_mul_f32_e32 v166, v166, v187
	v_mul_f32_e32 v167, v167, v187
	v_mul_f32_e32 v168, v168, v187
	v_mul_f32_e32 v169, v169, v187
	v_mul_f32_e32 v170, v170, v188
	v_mul_f32_e32 v171, v171, v188
	v_mul_f32_e32 v172, v172, v188
	v_mul_f32_e32 v173, v173, v188
	v_mul_f32_e32 v174, v174, v189
	v_mul_f32_e32 v175, v175, v189
	v_mul_f32_e32 v176, v176, v189
	v_mul_f32_e32 v177, v177, v189
	v_mul_f32_e32 v162, v58, v162
	v_mul_f32_e32 v163, v59, v163
	v_mul_f32_e32 v164, v60, v164
	v_mul_f32_e32 v165, v61, v165
	v_mul_f32_e32 v166, v58, v166
	v_mul_f32_e32 v167, v59, v167
	v_mul_f32_e32 v168, v60, v168
	v_mul_f32_e32 v169, v61, v169
	v_mul_f32_e32 v170, v58, v170
	v_mul_f32_e32 v171, v59, v171
	v_mul_f32_e32 v172, v60, v172
	v_mul_f32_e32 v173, v61, v173
	v_mul_f32_e32 v174, v58, v174
	v_mul_f32_e32 v175, v59, v175
	v_mul_f32_e32 v176, v60, v176
	v_mul_f32_e32 v177, v61, v177
	v_cvt_pk_bf16_f32 v182, v162, v163
	v_cvt_pk_bf16_f32 v183, v164, v165
	global_store_dwordx2 v8, v[182:183], s[58:59]
	v_cvt_pk_bf16_f32 v182, v166, v167
	v_cvt_pk_bf16_f32 v183, v168, v169
	global_store_dwordx2 v8, v[182:183], s[58:59] offset:2048
	v_add_u32_e32 v8, 0x1000, v8
	v_cvt_pk_bf16_f32 v182, v170, v171
	v_cvt_pk_bf16_f32 v183, v172, v173
	global_store_dwordx2 v8, v[182:183], s[58:59]
	v_cvt_pk_bf16_f32 v182, v174, v175
	v_cvt_pk_bf16_f32 v183, v176, v177
	global_store_dwordx2 v8, v[182:183], s[58:59] offset:2048
	v_add_u32_e32 v8, 0x1000, v8
	v_lshlrev_b32_e32 v70, 16, v22
	v_and_b32_e32 v71, 0xffff0000, v22
	v_lshlrev_b32_e32 v72, 16, v23
	v_and_b32_e32 v73, 0xffff0000, v23
	v_mul_f32_e32 v154, v46, v74
	v_mul_f32_e32 v155, v47, v75
	v_mul_f32_e32 v156, v48, v76
	v_mul_f32_e32 v157, v49, v77
	v_fmac_f32_e32 v154, v50, v78
	v_fmac_f32_e32 v155, v51, v79
	v_fmac_f32_e32 v156, v52, v80
	v_fmac_f32_e32 v157, v53, v81
	v_fmac_f32_e32 v154, v54, v70
	v_fmac_f32_e32 v155, v55, v71
	v_fmac_f32_e32 v156, v56, v72
	v_fmac_f32_e32 v157, v57, v73
	v_lshlrev_b32_e32 v158, 16, v32
	v_lshlrev_b32_e32 v159, 16, v36
	v_lshlrev_b32_e32 v160, 16, v40
	v_lshlrev_b32_e32 v161, 16, v44
	v_mul_f32_e32 v162, v154, v158
	v_mul_f32_e32 v163, v155, v159
	v_mul_f32_e32 v164, v156, v160
	v_mul_f32_e32 v165, v157, v161
	v_mul_f32_e32 v178, v162, v162
	v_fmac_f32_e32 v178, v163, v163
	v_fmac_f32_e32 v178, v164, v164
	v_fmac_f32_e32 v178, v165, v165
	v_lshlrev_b32_e32 v74, 16, v24
	v_and_b32_e32 v75, 0xffff0000, v24
	v_lshlrev_b32_e32 v76, 16, v25
	v_and_b32_e32 v77, 0xffff0000, v25
	v_mul_f32_e32 v154, v46, v78
	v_mul_f32_e32 v155, v47, v79
	v_mul_f32_e32 v156, v48, v80
	v_mul_f32_e32 v157, v49, v81
	v_fmac_f32_e32 v154, v50, v70
	v_fmac_f32_e32 v155, v51, v71
	v_fmac_f32_e32 v156, v52, v72
	v_fmac_f32_e32 v157, v53, v73
	v_fmac_f32_e32 v154, v54, v74
	v_fmac_f32_e32 v155, v55, v75
	v_fmac_f32_e32 v156, v56, v76
	v_fmac_f32_e32 v157, v57, v77
	v_and_b32_e32 v158, 0xffff0000, v32
	v_and_b32_e32 v159, 0xffff0000, v36
	v_and_b32_e32 v160, 0xffff0000, v40
	v_and_b32_e32 v161, 0xffff0000, v44
	v_mul_f32_e32 v166, v154, v158
	v_mul_f32_e32 v167, v155, v159
	v_mul_f32_e32 v168, v156, v160
	v_mul_f32_e32 v169, v157, v161
	v_mul_f32_e32 v179, v166, v166
	v_fmac_f32_e32 v179, v167, v167
	v_fmac_f32_e32 v179, v168, v168
	v_fmac_f32_e32 v179, v169, v169
	v_lshlrev_b32_e32 v78, 16, v26
	v_and_b32_e32 v79, 0xffff0000, v26
	v_lshlrev_b32_e32 v80, 16, v27
	v_and_b32_e32 v81, 0xffff0000, v27
	v_mul_f32_e32 v154, v46, v70
	v_mul_f32_e32 v155, v47, v71
	v_mul_f32_e32 v156, v48, v72
	v_mul_f32_e32 v157, v49, v73
	v_fmac_f32_e32 v154, v50, v74
	v_fmac_f32_e32 v155, v51, v75
	v_fmac_f32_e32 v156, v52, v76
	v_fmac_f32_e32 v157, v53, v77
	v_fmac_f32_e32 v154, v54, v78
	v_fmac_f32_e32 v155, v55, v79
	v_fmac_f32_e32 v156, v56, v80
	v_fmac_f32_e32 v157, v57, v81
	v_lshlrev_b32_e32 v158, 16, v33
	v_lshlrev_b32_e32 v159, 16, v37
	v_lshlrev_b32_e32 v160, 16, v41
	v_lshlrev_b32_e32 v161, 16, v45
	v_mul_f32_e32 v170, v154, v158
	v_mul_f32_e32 v171, v155, v159
	v_mul_f32_e32 v172, v156, v160
	v_mul_f32_e32 v173, v157, v161
	v_mul_f32_e32 v180, v170, v170
	v_fmac_f32_e32 v180, v171, v171
	v_fmac_f32_e32 v180, v172, v172
	v_fmac_f32_e32 v180, v173, v173
	v_lshlrev_b32_e32 v70, 16, v28
	v_and_b32_e32 v71, 0xffff0000, v28
	v_lshlrev_b32_e32 v72, 16, v29
	v_and_b32_e32 v73, 0xffff0000, v29
	v_mul_f32_e32 v154, v46, v74
	v_mul_f32_e32 v155, v47, v75
	v_mul_f32_e32 v156, v48, v76
	v_mul_f32_e32 v157, v49, v77
	v_fmac_f32_e32 v154, v50, v78
	v_fmac_f32_e32 v155, v51, v79
	v_fmac_f32_e32 v156, v52, v80
	v_fmac_f32_e32 v157, v53, v81
	v_fmac_f32_e32 v154, v66, v70
	v_fmac_f32_e32 v155, v67, v71
	v_fmac_f32_e32 v156, v68, v72
	v_fmac_f32_e32 v157, v69, v73
	v_and_b32_e32 v158, 0xffff0000, v33
	v_and_b32_e32 v159, 0xffff0000, v37
	v_and_b32_e32 v160, 0xffff0000, v41
	v_and_b32_e32 v161, 0xffff0000, v45
	v_mul_f32_e32 v174, v154, v158
	v_mul_f32_e32 v175, v155, v159
	v_mul_f32_e32 v176, v156, v160
	v_mul_f32_e32 v177, v157, v161
	v_mul_f32_e32 v181, v174, v174
	v_fmac_f32_e32 v181, v175, v175
	v_fmac_f32_e32 v181, v176, v176
	v_fmac_f32_e32 v181, v177, v177
	s_nop 1
	v_add_f32_dpp v178, v178, v178 quad_perm:[1,0,3,2] row_mask:0xf bank_mask:0xf
	v_add_f32_dpp v179, v179, v179 quad_perm:[1,0,3,2] row_mask:0xf bank_mask:0xf
	v_add_f32_dpp v180, v180, v180 quad_perm:[1,0,3,2] row_mask:0xf bank_mask:0xf
	v_add_f32_dpp v181, v181, v181 quad_perm:[1,0,3,2] row_mask:0xf bank_mask:0xf
	v_add_f32_dpp v178, v178, v178 quad_perm:[2,3,0,1] row_mask:0xf bank_mask:0xf
	v_add_f32_dpp v179, v179, v179 quad_perm:[2,3,0,1] row_mask:0xf bank_mask:0xf
	v_add_f32_dpp v180, v180, v180 quad_perm:[2,3,0,1] row_mask:0xf bank_mask:0xf
	v_add_f32_dpp v181, v181, v181 quad_perm:[2,3,0,1] row_mask:0xf bank_mask:0xf
	v_add_f32_dpp v178, v178, v178 row_half_mirror row_mask:0xf bank_mask:0xf
	v_add_f32_dpp v179, v179, v179 row_half_mirror row_mask:0xf bank_mask:0xf
	v_add_f32_dpp v180, v180, v180 row_half_mirror row_mask:0xf bank_mask:0xf
	v_add_f32_dpp v181, v181, v181 row_half_mirror row_mask:0xf bank_mask:0xf
	v_add_f32_dpp v178, v178, v178 row_mirror row_mask:0xf bank_mask:0xf
	v_add_f32_dpp v179, v179, v179 row_mirror row_mask:0xf bank_mask:0xf
	v_add_f32_dpp v180, v180, v180 row_mirror row_mask:0xf bank_mask:0xf
	v_add_f32_dpp v181, v181, v181 row_mirror row_mask:0xf bank_mask:0xf
	v_fmamk_f32 v186, v178, 0x3c800000, v194
	v_fmamk_f32 v187, v179, 0x3c800000, v194
	v_fmamk_f32 v188, v180, 0x3c800000, v194
	v_fmamk_f32 v189, v181, 0x3c800000, v194
	v_rsq_f32_e32 v186, v186
	v_rsq_f32_e32 v187, v187
	v_rsq_f32_e32 v188, v188
	v_rsq_f32_e32 v189, v189
	s_nop 0
	v_mul_f32_e32 v162, v162, v186
	v_mul_f32_e32 v163, v163, v186
	v_mul_f32_e32 v164, v164, v186
	v_mul_f32_e32 v165, v165, v186
	v_mul_f32_e32 v166, v166, v187
	v_mul_f32_e32 v167, v167, v187
	v_mul_f32_e32 v168, v168, v187
	v_mul_f32_e32 v169, v169, v187
	v_mul_f32_e32 v170, v170, v188
	v_mul_f32_e32 v171, v171, v188
	v_mul_f32_e32 v172, v172, v188
	v_mul_f32_e32 v173, v173, v188
	v_mul_f32_e32 v174, v174, v189
	v_mul_f32_e32 v175, v175, v189
	v_mul_f32_e32 v176, v176, v189
	v_mul_f32_e32 v177, v177, v189
	v_mul_f32_e32 v162, v58, v162
	v_mul_f32_e32 v163, v59, v163
	v_mul_f32_e32 v164, v60, v164
	v_mul_f32_e32 v165, v61, v165
	v_mul_f32_e32 v166, v58, v166
	v_mul_f32_e32 v167, v59, v167
	v_mul_f32_e32 v168, v60, v168
	v_mul_f32_e32 v169, v61, v169
	v_mul_f32_e32 v170, v58, v170
	v_mul_f32_e32 v171, v59, v171
	v_mul_f32_e32 v172, v60, v172
	v_mul_f32_e32 v173, v61, v173
	v_mul_f32_e32 v174, v58, v174
	v_mul_f32_e32 v175, v59, v175
	v_mul_f32_e32 v176, v60, v176
	v_mul_f32_e32 v177, v61, v177
	v_cvt_pk_bf16_f32 v182, v162, v163
	v_cvt_pk_bf16_f32 v183, v164, v165
	global_store_dwordx2 v8, v[182:183], s[58:59]
	v_cvt_pk_bf16_f32 v182, v166, v167
	v_cvt_pk_bf16_f32 v183, v168, v169
	global_store_dwordx2 v8, v[182:183], s[58:59] offset:2048
	v_add_u32_e32 v8, 0x1000, v8
	v_cvt_pk_bf16_f32 v182, v170, v171
	v_cvt_pk_bf16_f32 v183, v172, v173
	global_store_dwordx2 v8, v[182:183], s[58:59]
	v_cvt_pk_bf16_f32 v182, v174, v175
	v_cvt_pk_bf16_f32 v183, v176, v177
	global_store_dwordx2 v8, v[182:183], s[58:59] offset:2048
.LBB0_707:
	s_mov_b64 s[0:1], 0
.LBB0_708:
	s_and_b64 vcc, exec, s[0:1]
	s_cbranch_vccz .LBB0_812
	s_sub_i32 s0, s13, s30
	s_ashr_i32 s2, s0, 2
	s_abs_i32 s2, s2
	v_readlane_b32 s3, v254, 14
	s_mul_hi_u32 s3, s2, s3
	v_readlane_b32 s4, v254, 11
	s_mul_i32 s3, s3, s4
	s_sub_i32 s2, s2, s3
	s_and_b32 s1, s13, 3
	s_sub_i32 s3, s2, s4
	s_cmp_ge_u32 s2, s4
	s_cselect_b32 s2, s3, s2
	s_sub_i32 s3, s2, s4
	s_cmp_ge_u32 s2, s4
	s_cselect_b32 s2, s3, s2
	s_ashr_i32 s3, s0, 31
	s_xor_b32 s2, s2, s3
	s_sub_i32 s2, s2, s3
	v_readlane_b32 s4, v254, 22
	s_add_i32 s4, s2, s4
	s_abs_i32 s0, s0
	v_readlane_b32 s2, v254, 16
	s_mul_hi_u32 s2, s0, s2
	v_readlane_b32 s7, v254, 15
	s_mul_i32 s5, s2, s7
	s_sub_i32 s0, s0, s5
	s_add_i32 s5, s2, 1
	s_sub_i32 s6, s0, s7
	s_cmp_ge_u32 s0, s7
	s_cselect_b32 s2, s5, s2
	s_cselect_b32 s0, s6, s0
	s_add_i32 s5, s2, 1
	s_cmp_ge_u32 s0, s7
	s_cselect_b32 s0, s5, s2
	s_xor_b32 s0, s0, s3
	s_sub_i32 s5, s0, s3
	s_lshl_b32 s2, s4, 6
	s_lshl_b32 s0, s5, 8
	s_add_i32 s3, s2, 0xffffff00
	s_add_i32 s6, s0, 0x4000
	s_lshl_b32 s7, s5, 11
	s_cmp_lt_i32 s4, 4
	s_movk_i32 s0, 0x800
	s_mul_i32 s5, s5, 36
	s_cselect_b32 s0, 0x100, s0
	s_cselect_b32 s3, s2, s3
	s_cselect_b32 s2, s6, s7
	s_add_i32 s4, s5, s4
	v_mov_b32_e32 v52, v195
	v_readfirstlane_b32 s44, v195
	s_mov_b32 s47, s0
	s_mov_b32 s48, s2
	s_mov_b32 s49, s3
	s_lshl_b32 s50, s1, 7
	s_lshr_b32 s44, s44, 6
	s_lshl_b32 s45, s44, 3
	s_add_i32 s45, s45, s49
	s_add_i32 s46, s47, -1
	s_addk_i32 s50, 0x1600
	v_and_b32_e32 v185, 63, v195
	v_lshl_add_u32 v180, v185, 1, s50
	v_readlane_b32 s52, v254, 3
	v_readlane_b32 s53, v254, 4
	s_lshl_b32 s51, s1, 8
	v_lshl_add_u32 v181, v185, 2, s51
	s_nop 2
	global_load_dword v165, v181, s[52:53]
	s_nop 1
	global_load_dword v166, v181, s[52:53] offset:1024
	s_nop 0
	global_load_dword v167, v181, s[52:53] offset:2048
	global_load_dword v168, v181, s[52:53] offset:3072
	s_add_i32 s54, s45, s48
	s_mul_i32 s54, s54, 0x1a00
	s_and_b32 s56, s13, 3
	v_bfe_u32 v208, v195, 4, 2
	v_and_b32_e32 v209, 15, v195
	v_mul_u32_u24_e32 v210, 0x1a00, v208
	v_lshl_add_u32 v210, v209, 3, v210
	s_add_i32 s57, s54, s50
	s_addk_i32 s57, 0x200
	v_add_u32_e32 v210, s57, v210
	v_readlane_b32 s58, v254, 9
	v_readlane_b32 s59, v254, 10
	global_load_dwordx2 v[204:205], v210, s[88:89]
	v_add_u32_e32 v210, 0x6800, v210
	global_load_dwordx2 v[206:207], v210, s[88:89]
	s_lshl_b32 s57, s56, 8
	s_addk_i32 s57, 0xc00
	v_lshl_add_u32 v211, v209, 4, s57
	global_load_dwordx4 v[200:203], v211, s[58:59]
	v_add_u32_e32 v181, s54, v180
	s_add_i32 s55, s45, -1
	s_max_i32 s55, s55, 0
	s_add_i32 s55, s55, s48
	s_mul_i32 s55, s55, 0x1a00
	v_add_u32_e32 v184, s55, v180
	global_load_ushort v154, v184, s[88:89]
	global_load_ushort v155, v181, s[88:89]
	v_add_u32_e32 v181, 0x1a00, v181
	global_load_ushort v156, v181, s[88:89]
	v_add_u32_e32 v181, 0x1a00, v181
	global_load_ushort v157, v181, s[88:89]
	v_add_u32_e32 v181, 0x1a00, v181
	global_load_ushort v158, v181, s[88:89]
	v_add_u32_e32 v181, 0x1a00, v181
	global_load_ushort v159, v181, s[88:89]
	v_add_u32_e32 v181, 0x1a00, v181
	global_load_ushort v160, v181, s[88:89]
	v_add_u32_e32 v181, 0x1a00, v181
	global_load_ushort v161, v181, s[88:89]
	v_add_u32_e32 v181, 0x1a00, v181
	global_load_ushort v162, v181, s[88:89]
	s_add_i32 s55, s45, 8
	s_min_i32 s55, s55, s46
	s_add_i32 s55, s55, s48
	s_mul_i32 s55, s55, 0x1a00
	v_add_u32_e32 v184, s55, v180
	global_load_ushort v163, v184, s[88:89]
	s_add_i32 s55, s45, 9
	s_min_i32 s55, s55, s46
	s_add_i32 s55, s55, s48
	s_mul_i32 s55, s55, 0x1a00
	v_add_u32_e32 v184, s55, v180
	global_load_ushort v164, v184, s[88:89]
	s_mul_i32 s55, s44, 0x820
	v_lshl_add_u32 v182, v185, 2, s55
	s_mul_i32 s55, s44, 0x480
	v_lshl_add_u32 v183, v185, 1, s55
	s_ashr_i32 s5, s4, 31
	s_lshl_b32 s7, s1, 6
	v_ashrrev_i32_e32 v47, 6, v52
	s_lshl_b64 s[4:5], s[4:5], 11
	v_readlane_b32 s8, v252, 11
	v_and_b32_e32 v48, 1, v47
	v_readlane_b32 s9, v252, 12
	s_add_u32 s4, s8, s4
	s_addc_u32 s5, s9, s5
	v_lshlrev_b32_e32 v192, 10, v48
	v_and_b32_e32 v29, 63, v52
	v_lshl_add_u64 v[0:1], s[4:5], 0, v[192:193]
	s_lshl_b32 s96, s1, 8
	v_lshl_add_u64 v[0:1], v[0:1], 0, s[96:97]
	v_lshlrev_b32_e32 v192, 2, v29
	s_add_i32 s4, s3, s2
	v_lshlrev_b32_e32 v12, 3, v47
	v_lshl_add_u64 v[2:3], v[0:1], 0, v[192:193]
	v_add_u32_e32 v28, s4, v12
	v_mov_b64_e32 v[0:1], s[88:89]
	s_lshl_b32 s96, s1, 7
	s_movk_i32 s10, 0x1000
	global_load_dword v51, v[2:3], off
	s_add_i32 s6, s2, -1
	v_or_b32_e32 v7, s7, v29
	v_lshlrev_b32_e32 v32, 1, v7
	v_mov_b32_e32 v33, v193
	v_lshlrev_b32_e32 v39, 2, v7
	s_add_i32 s5, s0, -1
	v_and_b32_e32 v6, 15, v52
	v_lshlrev_b32_e32 v2, 4, v47
	v_ashrrev_i32_e32 v56, 8, v52
	v_and_or_b32 v55, v2, 48, v6
	v_lshlrev_b32_e32 v2, 9, v56
	v_readlane_b32 s8, v254, 12
	v_lshl_or_b32 v7, v56, 1, 1
	v_or_b32_e32 v4, s7, v55
	v_ashrrev_i32_e32 v3, 31, v2
	v_readlane_b32 s9, v254, 13
	v_lshlrev_b32_e32 v16, 8, v7
	v_lshlrev_b32_e32 v4, 2, v4
	v_lshl_add_u64 v[2:3], v[2:3], 2, s[8:9]
	v_mov_b32_e32 v5, v193
	v_ashrrev_i32_e32 v17, 31, v16
	v_lshl_add_u64 v[2:3], v[2:3], 0, v[4:5]
	v_lshl_add_u64 v[16:17], v[16:17], 2, s[8:9]
	v_lshl_add_u64 v[16:17], v[16:17], 0, v[4:5]
	global_load_dword v54, v[2:3], off
	global_load_dword v53, v[16:17], off
	v_and_b32_e32 v2, 0xffffff00, v52
	v_readlane_b32 s8, v254, 1
	v_ashrrev_i32_e32 v3, 31, v2
	v_readlane_b32 s9, v254, 2
	v_or_b32_e32 v37, 1, v12
	v_add_u32_e32 v30, 0, v192
	v_lshl_add_u64 v[2:3], v[2:3], 2, s[8:9]
	v_lshl_add_u64 v[2:3], v[2:3], 0, v[4:5]
	global_load_dword v16, v[2:3], off
	v_or_b32_e32 v38, 2, v12
	v_or_b32_e32 v40, 3, v12
	v_or_b32_e32 v43, 4, v12
	s_movk_i32 s12, 0x104
	s_movk_i32 s11, 0x90
	v_or_b32_e32 v44, 5, v12
	v_or_b32_e32 v45, 6, v12
	v_add_u32_e32 v68, s3, v45
	v_add_u32_e32 v69, 2, v68
	v_min_i32_e32 v26, s5, v69
	v_or_b32_e32 v46, 7, v12
	v_add_u32_e32 v13, s2, v26
	v_add_u32_e32 v70, s3, v46
	v_mad_i64_i32 v[26:27], s[8:9], v13, s92, v[0:1]
	v_max_i32_e32 v12, 1, v70
	v_add_u32_e32 v12, s6, v12
	v_mad_u64_u32 v[12:13], s[6:7], v12, s92, v[0:1]
	v_lshl_add_u64 v[12:13], v[12:13], 0, v[32:33]
	v_add_u32_e32 v58, s2, v70
	v_add_co_u32_e32 v12, vcc, s10, v12
	v_mad_i64_i32 v[58:59], s[6:7], v58, s92, v[0:1]
	s_nop 0
	v_addc_co_u32_e32 v13, vcc, 0, v13, vcc
	v_ashrrev_i32_e32 v80, 3, v52
	global_load_ushort v78, v[12:13], off offset:1536
	v_readlane_b32 s2, v254, 5
	v_lshlrev_b32_e32 v12, 4, v52
	v_ashrrev_i32_e32 v33, 7, v52
	s_or_b32 s1, s1, s2
	v_and_b32_e32 v26, 0x70, v12
	v_and_b32_e32 v12, -4, v33
	v_add_u32_e32 v12, s1, v12
	v_ashrrev_i32_e32 v13, 31, v12
	v_readlane_b32 s2, v251, 22
	v_lshlrev_b64 v[12:13], 13, v[12:13]
	v_readlane_b32 s3, v251, 23
	v_lshlrev_b32_e32 v14, 7, v80
	v_and_b32_e32 v14, 0x1f80, v14
	v_lshl_add_u64 v[12:13], s[2:3], 0, v[12:13]
	v_mov_b32_e32 v15, v193
	v_lshl_add_u64 v[12:13], v[12:13], 0, v[14:15]
	v_mov_b32_e32 v27, v193
	v_lshl_add_u64 v[12:13], v[12:13], 0, v[26:27]
	global_load_dwordx4 v[12:15], v[12:13], off
	v_add_u32_e32 v0, 0x200, v52
	v_ashrrev_i32_e32 v82, 3, v0
	v_ashrrev_i32_e32 v0, 7, v0
	v_and_b32_e32 v0, -4, v0
	v_add_u32_e32 v0, s1, v0
	v_ashrrev_i32_e32 v1, 31, v0
	v_lshlrev_b64 v[0:1], 13, v[0:1]
	v_lshlrev_b32_e32 v18, 7, v82
	v_lshl_add_u64 v[0:1], s[2:3], 0, v[0:1]
	v_and_b32_e32 v18, 0x1f80, v18
	v_mov_b32_e32 v19, v193
	v_lshl_add_u64 v[0:1], v[0:1], 0, v[18:19]
	v_add_u32_e32 v18, 0x400, v52
	v_ashrrev_i32_e32 v83, 3, v18
	v_ashrrev_i32_e32 v18, 7, v18
	v_and_b32_e32 v18, -4, v18
	v_add_u32_e32 v18, s1, v18
	v_ashrrev_i32_e32 v19, 31, v18
	v_lshlrev_b64 v[18:19], 13, v[18:19]
	v_lshlrev_b32_e32 v20, 7, v83
	v_lshl_add_u64 v[18:19], s[2:3], 0, v[18:19]
	v_and_b32_e32 v20, 0x1f80, v20
	v_mov_b32_e32 v21, v193
	v_lshl_add_u64 v[18:19], v[18:19], 0, v[20:21]
	v_lshl_add_u64 v[0:1], v[0:1], 0, v[26:27]
	v_lshl_add_u64 v[22:23], v[18:19], 0, v[26:27]
	global_load_dwordx4 v[18:21], v[0:1], off
	global_load_dwordx4 v[22:25], v[22:23], off
	v_add_u32_e32 v0, 0x600, v52
	v_ashrrev_i32_e32 v84, 3, v0
	v_ashrrev_i32_e32 v0, 7, v0
	v_and_b32_e32 v0, -4, v0
	v_add_u32_e32 v0, s1, v0
	v_ashrrev_i32_e32 v1, 31, v0
	v_lshlrev_b64 v[0:1], 13, v[0:1]
	v_lshlrev_b32_e32 v58, 7, v84
	v_lshl_add_u64 v[0:1], s[2:3], 0, v[0:1]
	v_and_b32_e32 v58, 0x1f80, v58
	v_mov_b32_e32 v59, v193
	v_lshl_add_u64 v[0:1], v[0:1], 0, v[58:59]
	v_lshl_add_u64 v[0:1], v[0:1], 0, v[26:27]
	global_load_dwordx4 v[58:61], v[0:1], off
	s_waitcnt vmcnt(0)
	v_lshlrev_b32_e32 v1, 16, v78
	v_add_u32_e32 v0, 0, v26
	v_mad_u64_u32 v[2:3], s[0:1], v80, s11, v[0:1]
	ds_write_b128 v2, v[12:15] offset:25856
	v_mad_u64_u32 v[2:3], s[0:1], v82, s11, v[0:1]
	ds_write_b128 v2, v[18:21] offset:25856
	v_mad_u64_u32 v[2:3], s[0:1], v83, s11, v[0:1]
	v_mad_u64_u32 v[0:1], s[0:1], v84, s11, v[0:1]
	ds_write_b128 v2, v[22:25] offset:25856
	ds_write_b128 v0, v[58:61] offset:25856
	v_and_b32_e32 v0, 48, v52
	v_add_u32_e32 v0, 0, v0
	v_mad_u32_u24 v17, v6, s11, v0
	s_waitcnt vmcnt(0)
	v_lshlrev_b32_e32 v154, 16, v154
	v_lshlrev_b32_e32 v155, 16, v155
	v_lshlrev_b32_e32 v156, 16, v156
	v_lshlrev_b32_e32 v157, 16, v157
	v_lshlrev_b32_e32 v158, 16, v158
	v_lshlrev_b32_e32 v159, 16, v159
	v_lshlrev_b32_e32 v160, 16, v160
	v_lshlrev_b32_e32 v161, 16, v161
	v_lshlrev_b32_e32 v162, 16, v162
	v_lshlrev_b32_e32 v163, 16, v163
	v_lshlrev_b32_e32 v164, 16, v164
	s_cmp_ge_i32 s45, 1
	s_cselect_b64 s[56:57], -1, 0
	s_add_i32 s55, s45, 8
	s_cmp_lt_i32 s55, s47
	s_cselect_b64 s[58:59], -1, 0
	v_cndmask_b32_e64 v169, 0, v165, s[56:57]
	v_cndmask_b32_e64 v170, 0, v167, s[58:59]
	v_cndmask_b32_e64 v171, 0, v168, s[58:59]
	v_mul_f32_e32 v172, v166, v155
	v_fmac_f32_e32 v172, v169, v154
	v_fmac_f32_e32 v172, v167, v156
	v_fmac_f32_e32 v172, v168, v157
	v_mul_f32_e32 v173, v166, v156
	v_fmac_f32_e32 v173, v165, v155
	v_fmac_f32_e32 v173, v167, v157
	v_fmac_f32_e32 v173, v168, v158
	v_mul_f32_e32 v174, v166, v157
	v_fmac_f32_e32 v174, v165, v156
	v_fmac_f32_e32 v174, v167, v158
	v_fmac_f32_e32 v174, v168, v159
	v_mul_f32_e32 v175, v166, v158
	v_fmac_f32_e32 v175, v165, v157
	v_fmac_f32_e32 v175, v167, v159
	v_fmac_f32_e32 v175, v168, v160
	v_mul_f32_e32 v176, v166, v159
	v_fmac_f32_e32 v176, v165, v158
	v_fmac_f32_e32 v176, v167, v160
	v_fmac_f32_e32 v176, v168, v161
	v_mul_f32_e32 v177, v166, v160
	v_fmac_f32_e32 v177, v165, v159
	v_fmac_f32_e32 v177, v167, v161
	v_fmac_f32_e32 v177, v168, v162
	v_mul_f32_e32 v178, v166, v161
	v_fmac_f32_e32 v178, v165, v160
	v_fmac_f32_e32 v178, v167, v162
	v_fmac_f32_e32 v178, v171, v163
	v_mul_f32_e32 v179, v166, v162
	v_fmac_f32_e32 v179, v165, v161
	v_fmac_f32_e32 v179, v170, v163
	v_fmac_f32_e32 v179, v171, v164
	v_cvt_pk_bf16_f32 v184, v172, v172
	ds_write_b32 v182, v172
	ds_write_b16 v183, v184 offset:16640
	v_cvt_pk_bf16_f32 v184, v173, v173
	ds_write_b32 v182, v173 offset:260
	ds_write_b16 v183, v184 offset:16784
	v_cvt_pk_bf16_f32 v184, v174, v174
	ds_write_b32 v182, v174 offset:520
	ds_write_b16 v183, v184 offset:16928
	v_cvt_pk_bf16_f32 v184, v175, v175
	ds_write_b32 v182, v175 offset:780
	ds_write_b16 v183, v184 offset:17072
	v_cvt_pk_bf16_f32 v184, v176, v176
	ds_write_b32 v182, v176 offset:1040
	ds_write_b16 v183, v184 offset:17216
	v_cvt_pk_bf16_f32 v184, v177, v177
	ds_write_b32 v182, v177 offset:1300
	ds_write_b16 v183, v184 offset:17360
	v_cvt_pk_bf16_f32 v184, v178, v178
	ds_write_b32 v182, v178 offset:1560
	ds_write_b16 v183, v184 offset:17504
	v_cvt_pk_bf16_f32 v184, v179, v179
	ds_write_b32 v182, v179 offset:1820
	ds_write_b16 v183, v184 offset:17648
	s_waitcnt lgkmcnt(0)
	s_barrier
	ds_read_b128 v[18:21], v17 offset:16640
	v_lshl_or_b32 v1, v56, 7, v55
	v_mad_u64_u32 v[2:3], s[0:1], v1, s11, v[0:1]
	v_lshl_or_b32 v1, v7, 6, v55
	ds_read_b128 v[12:15], v2 offset:25856
	v_mad_u64_u32 v[0:1], s[0:1], v1, s11, v[0:1]
	ds_read_b128 v[4:7], v2 offset:25920
	ds_read_b128 v[22:25], v17 offset:16704
	ds_read_b128 v[8:11], v0 offset:25856
	ds_read_b128 v[0:3], v0 offset:25920
	s_mov_b32 s0, 0xbfb8aa3b
	v_mul_f32_e64 v26, |v16|, s0
	s_waitcnt lgkmcnt(4)
	v_mfma_f32_16x16x32_bf16 v[58:61], v[18:21], v[12:15], 0
	v_exp_f32_e32 v26, v26
	s_mov_b32 s0, 0x800000
	v_max_f32_e64 v16, -v16, -v16
	s_waitcnt lgkmcnt(1)
	v_mfma_f32_16x16x32_bf16 v[18:21], v[18:21], v[8:11], 0
	v_max_f32_e32 v16, 0, v16
	v_bfe_u32 v82, v52, 4, 2
	ds_read_b128 v[62:65], v17 offset:18944
	ds_read_b128 v[66:69], v17 offset:19008
	s_waitcnt lgkmcnt(2)
	v_mfma_f32_16x16x32_bf16 v[74:77], v[22:25], v[0:3], v[18:21]
	v_lshlrev_b32_e32 v56, 12, v56
	v_and_b32_e32 v52, 0x1fffff80, v52
	s_nop 0
	v_add_f32_e32 v18, 1.0, v26
	v_cmp_gt_f32_e32 vcc, s0, v18
	v_mfma_f32_16x16x32_bf16 v[58:61], v[22:25], v[4:7], v[58:61]
	s_mov_b32 s0, 0x3f317217
	v_cndmask_b32_e64 v19, 0, 32, vcc
	v_ldexp_f32 v18, v18, v19
	v_log_f32_e32 v18, v18
	v_mov_b32_e32 v20, 0x41b17218
	v_cndmask_b32_e32 v20, 0, v20, vcc
	s_nop 1
	v_add_f32_e32 v59, v54, v59
	v_mul_f32_e32 v19, 0x3f317217, v18
	v_fma_f32 v19, v18, s0, -v19
	v_fmac_f32_e32 v19, 0x3377d1cf, v18
	s_mov_b32 s0, 0x7f800000
	v_fmac_f32_e32 v19, 0x3f317217, v18
	v_cmp_lt_f32_e64 s[0:1], |v18|, s0
	ds_read_b128 v[78:81], v17 offset:21248
	ds_read_b128 v[24:27], v17 offset:21312
	v_cndmask_b32_e64 v18, v18, v19, s[0:1]
	v_add_f32_e32 v19, v54, v58
	v_mul_f32_e32 v19, 0xbfb8aa3b, v19
	v_exp_f32_e32 v19, v19
	v_sub_f32_e32 v18, v18, v20
	v_add_f32_e32 v57, v16, v18
	v_add_f32_e32 v18, v53, v74
	v_add_f32_e32 v16, 1.0, v19
	v_rcp_f32_e32 v16, v16
	v_mul_f32_e32 v18, 0xbfb8aa3b, v18
	v_exp_f32_e32 v18, v18
	v_lshl_add_u32 v74, v55, 2, 0
	v_mul_f32_e32 v16, 0xc1000000, v16
	v_mul_f32_e32 v16, v57, v16
	v_mul_f32_e32 v16, 0x3fb8aa3b, v16
	v_exp_f32_e32 v58, v16
	v_add_f32_e32 v16, 1.0, v18
	v_rcp_f32_e32 v83, v16
	s_movk_i32 s0, 0x410
	v_fma_f32 v16, -v58, v58, 1.0
	v_max_f32_e32 v16, 0, v16
	v_sqrt_f32_e32 v84, v16
	v_mad_u32_u24 v16, v82, s0, v74
	ds_read_b32 v85, v16
	ds_read_b128 v[20:23], v17 offset:23552
	ds_read_b128 v[16:19], v17 offset:23616
	v_mul_f32_e32 v59, 0xbfb8aa3b, v59
	v_mul_f32_e32 v83, v83, v84
	v_lshlrev_b32_e32 v84, 8, v82
	v_or3_b32 v84, v84, v56, v55
	v_exp_f32_e32 v59, v59
	v_lshlrev_b32_e32 v84, 2, v84
	s_waitcnt lgkmcnt(2)
	v_mul_f32_e32 v83, v85, v83
	v_add_u32_e32 v85, 0, v84
	v_readlane_b32 s0, v253, 37
	ds_write_b32 v85, v58 offset:62720
	v_mfma_f32_16x16x32_bf16 v[70:73], v[62:65], v[12:15], 0
	v_add_u32_e32 v58, s0, v84
	ds_write_b32 v58, v83
	v_add_f32_e32 v58, 1.0, v59
	v_add_f32_e32 v59, v53, v75
	v_lshl_or_b32 v75, v82, 2, 1
	v_rcp_f32_e32 v58, v58
	v_mad_u32_u24 v74, v75, s12, v74
	v_lshlrev_b32_e32 v75, 6, v75
	v_or3_b32 v55, v75, v56, v55
	v_add_f32_e32 v56, v54, v60
	v_mul_f32_e32 v56, 0xbfb8aa3b, v56
	v_exp_f32_e32 v56, v56
	v_mul_f32_e32 v58, 0xc1000000, v58
	v_mul_f32_e32 v58, v57, v58
	v_mul_f32_e32 v58, 0x3fb8aa3b, v58
	v_mul_f32_e32 v59, 0xbfb8aa3b, v59
	v_exp_f32_e32 v58, v58
	v_add_f32_e32 v56, 1.0, v56
	v_exp_f32_e32 v59, v59
	v_rcp_f32_e32 v56, v56
	v_fma_f32 v82, -v58, v58, 1.0
	v_lshlrev_b32_e32 v55, 2, v55
	v_add_f32_e32 v59, 1.0, v59
	v_max_f32_e32 v82, 0, v82
	v_add_u32_e32 v60, 0, v55
	v_mul_f32_e32 v56, 0xc1000000, v56
	v_rcp_f32_e32 v59, v59
	v_sqrt_f32_e32 v82, v82
	ds_read_b32 v83, v74
	ds_write_b32 v60, v58 offset:62720
	v_add_f32_e32 v58, v53, v76
	v_mul_f32_e32 v56, v57, v56
	v_mul_f32_e32 v58, 0xbfb8aa3b, v58
	v_mul_f32_e32 v56, 0x3fb8aa3b, v56
	v_exp_f32_e32 v58, v58
	v_exp_f32_e32 v56, v56
	v_mul_f32_e32 v59, v59, v82
	s_waitcnt lgkmcnt(1)
	v_mul_f32_e32 v59, v83, v59
	v_add_u32_e32 v55, s0, v55
	ds_write_b32 v55, v59
	v_add_f32_e32 v55, 1.0, v58
	v_fma_f32 v58, -v56, v56, 1.0
	v_max_f32_e32 v58, 0, v58
	v_rcp_f32_e32 v55, v55
	v_sqrt_f32_e32 v58, v58
	ds_read_b32 v59, v74 offset:260
	v_mfma_f32_16x16x32_bf16 v[62:65], v[62:65], v[8:11], 0
	v_cmp_eq_u32_e32 vcc, 0, v48
	v_mul_f32_e32 v55, v55, v58
	v_or_b32_e32 v58, 0x200, v84
	s_waitcnt lgkmcnt(0)
	v_mul_f32_e32 v55, v55, v59
	v_add_f32_e32 v59, v54, v61
	v_mul_f32_e32 v59, 0xbfb8aa3b, v59
	v_exp_f32_e32 v59, v59
	v_add_u32_e32 v60, 0, v58
	ds_write_b32 v60, v56 offset:62720
	v_add_u32_e32 v56, s0, v58
	v_add_f32_e32 v58, 1.0, v59
	v_rcp_f32_e32 v58, v58
	v_add_f32_e32 v59, v53, v77
	v_mul_f32_e32 v59, 0xbfb8aa3b, v59
	v_mfma_f32_16x16x32_bf16 v[70:73], v[66:69], v[4:7], v[70:73]
	v_exp_f32_e32 v59, v59
	v_mul_f32_e32 v58, 0xc1000000, v58
	v_mul_f32_e32 v58, v57, v58
	v_mul_f32_e32 v58, 0x3fb8aa3b, v58
	v_exp_f32_e32 v75, v58
	ds_write_b32 v56, v55
	v_add_f32_e32 v55, 1.0, v59
	v_mfma_f32_16x16x32_bf16 v[58:61], v[66:69], v[0:3], v[62:65]
	v_fma_f32 v56, -v75, v75, 1.0
	v_max_f32_e32 v56, 0, v56
	v_rcp_f32_e32 v55, v55
	v_add_f32_e32 v62, v54, v70
	v_mul_f32_e32 v62, 0xbfb8aa3b, v62
	v_exp_f32_e32 v62, v62
	v_sqrt_f32_e32 v56, v56
	ds_read_b32 v76, v74 offset:520
	v_add_f32_e32 v58, v53, v58
	v_add_f32_e32 v62, 1.0, v62
	v_rcp_f32_e32 v62, v62
	v_mul_f32_e32 v58, 0xbfb8aa3b, v58
	v_exp_f32_e32 v58, v58
	v_mul_f32_e32 v55, v55, v56
	v_mul_f32_e32 v62, 0xc1000000, v62
	v_mul_f32_e32 v62, v57, v62
	v_mul_f32_e32 v62, 0x3fb8aa3b, v62
	v_exp_f32_e32 v66, v62
	v_or_b32_e32 v56, 0x300, v84
	s_waitcnt lgkmcnt(0)
	v_mul_f32_e32 v55, v55, v76
	v_add_u32_e32 v63, 0, v56
	v_add_u32_e32 v56, s0, v56
	ds_write_b32 v56, v55
	v_fma_f32 v56, -v66, v66, 1.0
	ds_write_b32 v63, v75 offset:62720
	v_add_f32_e32 v55, 1.0, v58
	v_max_f32_e32 v56, 0, v56
	v_rcp_f32_e32 v55, v55
	v_sqrt_f32_e32 v56, v56
	ds_read_b32 v58, v74 offset:3900
	v_add_f32_e32 v59, v53, v59
	v_mul_f32_e32 v59, 0xbfb8aa3b, v59
	v_mul_f32_e32 v55, v55, v56
	v_exp_f32_e32 v59, v59
	s_waitcnt lgkmcnt(0)
	v_mul_f32_e32 v55, v55, v58
	v_add_f32_e32 v58, v54, v71
	v_mul_f32_e32 v58, 0xbfb8aa3b, v58
	v_exp_f32_e32 v58, v58
	v_or_b32_e32 v56, 0x1000, v84
	v_add_u32_e32 v67, 0, v56
	v_add_u32_e32 v56, s0, v56
	v_add_f32_e32 v58, 1.0, v58
	v_rcp_f32_e32 v58, v58
	ds_write_b32 v56, v55
	ds_write_b32 v67, v66 offset:62720
	v_add_f32_e32 v55, 1.0, v59
	v_mul_f32_e32 v58, 0xc1000000, v58
	v_mul_f32_e32 v58, v57, v58
	v_mul_f32_e32 v58, 0x3fb8aa3b, v58
	v_exp_f32_e32 v58, v58
	v_rcp_f32_e32 v55, v55
	ds_read_b32 v59, v74 offset:4160
	v_mfma_f32_16x16x32_bf16 v[62:65], v[78:81], v[12:15], 0
	v_fma_f32 v56, -v58, v58, 1.0
	v_max_f32_e32 v56, 0, v56
	v_sqrt_f32_e32 v56, v56
	v_mfma_f32_16x16x32_bf16 v[62:65], v[24:27], v[4:7], v[62:65]
	v_mul_f32_e32 v55, v55, v56
	s_waitcnt lgkmcnt(0)
	v_mul_f32_e32 v55, v55, v59
	v_add_f32_e32 v59, v54, v72
	v_mul_f32_e32 v59, 0xbfb8aa3b, v59
	v_exp_f32_e32 v59, v59
	v_or_b32_e32 v56, 0x1100, v84
	v_add_u32_e32 v70, 0, v56
	ds_write_b32 v70, v58 offset:62720
	v_add_f32_e32 v58, 1.0, v59
	v_rcp_f32_e32 v58, v58
	v_add_f32_e32 v59, v53, v60
	v_mul_f32_e32 v59, 0xbfb8aa3b, v59
	v_exp_f32_e32 v59, v59
	v_mul_f32_e32 v58, 0xc1000000, v58
	v_mul_f32_e32 v58, v57, v58
	v_mul_f32_e32 v58, 0x3fb8aa3b, v58
	v_exp_f32_e32 v58, v58
	v_add_u32_e32 v56, s0, v56
	ds_write_b32 v56, v55
	v_add_f32_e32 v55, 1.0, v59
	v_fma_f32 v56, -v58, v58, 1.0
	v_max_f32_e32 v56, 0, v56
	v_rcp_f32_e32 v55, v55
	v_sqrt_f32_e32 v56, v56
	ds_read_b32 v59, v74 offset:4420
	v_mfma_f32_16x16x32_bf16 v[66:69], v[78:81], v[8:11], 0
	v_mul_f32_e32 v55, v55, v56
	v_or_b32_e32 v56, 0x1200, v84
	s_waitcnt lgkmcnt(0)
	v_mul_f32_e32 v55, v55, v59
	v_add_f32_e32 v59, v54, v73
	v_mul_f32_e32 v59, 0xbfb8aa3b, v59
	v_exp_f32_e32 v59, v59
	v_add_u32_e32 v60, 0, v56
	ds_write_b32 v60, v58 offset:62720
	v_add_u32_e32 v56, s0, v56
	v_add_f32_e32 v58, 1.0, v59
	v_rcp_f32_e32 v58, v58
	v_add_f32_e32 v59, v53, v61
	v_mul_f32_e32 v59, 0xbfb8aa3b, v59
	v_exp_f32_e32 v59, v59
	v_mul_f32_e32 v58, 0xc1000000, v58
	v_mul_f32_e32 v58, v57, v58
	v_mul_f32_e32 v58, 0x3fb8aa3b, v58
	v_exp_f32_e32 v58, v58
	ds_write_b32 v56, v55
	v_add_f32_e32 v55, 1.0, v59
	v_rcp_f32_e32 v55, v55
	v_fma_f32 v56, -v58, v58, 1.0
	v_max_f32_e32 v56, 0, v56
	v_sqrt_f32_e32 v56, v56
	ds_read_b32 v59, v74 offset:4680
	v_mfma_f32_16x16x32_bf16 v[24:27], v[24:27], v[0:3], v[66:69]
	v_mul_f32_e32 v55, v55, v56
	v_or_b32_e32 v56, 0x1300, v84
	s_waitcnt lgkmcnt(0)
	v_mul_f32_e32 v55, v55, v59
	v_add_f32_e32 v59, v54, v62
	v_mul_f32_e32 v59, 0xbfb8aa3b, v59
	v_exp_f32_e32 v59, v59
	v_add_u32_e32 v60, 0, v56
	ds_write_b32 v60, v58 offset:62720
	v_add_f32_e32 v24, v53, v24
	v_add_f32_e32 v58, 1.0, v59
	v_rcp_f32_e32 v58, v58
	v_mul_f32_e32 v24, 0xbfb8aa3b, v24
	v_exp_f32_e32 v24, v24
	v_add_u32_e32 v56, s0, v56
	v_mul_f32_e32 v58, 0xc1000000, v58
	v_mul_f32_e32 v58, v57, v58
	v_mul_f32_e32 v58, 0x3fb8aa3b, v58
	v_exp_f32_e32 v58, v58
	ds_write_b32 v56, v55
	v_add_f32_e32 v24, 1.0, v24
	v_rcp_f32_e32 v24, v24
	v_fma_f32 v55, -v58, v58, 1.0
	v_max_f32_e32 v55, 0, v55
	v_sqrt_f32_e32 v55, v55
	ds_read_b32 v56, v74 offset:8060
	v_mfma_f32_16x16x32_bf16 v[12:15], v[20:23], v[12:15], 0
	v_add_f32_e32 v25, v53, v25
	v_mul_f32_e32 v24, v24, v55
	v_mul_f32_e32 v25, 0xbfb8aa3b, v25
	s_waitcnt lgkmcnt(0)
	v_mul_f32_e32 v24, v24, v56
	v_add_f32_e32 v56, v54, v63
	v_mul_f32_e32 v56, 0xbfb8aa3b, v56
	v_exp_f32_e32 v56, v56
	v_mfma_f32_16x16x32_bf16 v[8:11], v[20:23], v[8:11], 0
	v_add_f32_e32 v22, v54, v64
	v_mul_f32_e32 v22, 0xbfb8aa3b, v22
	v_add_f32_e32 v56, 1.0, v56
	v_rcp_f32_e32 v56, v56
	v_exp_f32_e32 v22, v22
	v_exp_f32_e32 v25, v25
	v_or_b32_e32 v55, 0x2000, v84
	v_mul_f32_e32 v56, 0xc1000000, v56
	v_mul_f32_e32 v56, v57, v56
	v_mul_f32_e32 v56, 0x3fb8aa3b, v56
	v_exp_f32_e32 v56, v56
	v_add_f32_e32 v22, 1.0, v22
	v_rcp_f32_e32 v22, v22
	v_mfma_f32_16x16x32_bf16 v[4:7], v[16:19], v[4:7], v[12:15]
	v_add_u32_e32 v59, 0, v55
	v_add_u32_e32 v55, s0, v55
	ds_write_b32 v55, v24
	v_add_f32_e32 v14, v54, v65
	v_mul_f32_e32 v14, 0xbfb8aa3b, v14
	v_add_f32_e32 v24, 1.0, v25
	v_fma_f32 v25, -v56, v56, 1.0
	v_exp_f32_e32 v14, v14
	ds_write_b32 v59, v58 offset:62720
	v_max_f32_e32 v25, 0, v25
	v_or_b32_e32 v21, 0x2100, v84
	v_mul_f32_e32 v22, 0xc1000000, v22
	v_rcp_f32_e32 v24, v24
	v_sqrt_f32_e32 v25, v25
	ds_read_b32 v55, v74 offset:8320
	v_add_u32_e32 v23, 0, v21
	v_mul_f32_e32 v22, v57, v22
	ds_write_b32 v23, v56 offset:62720
	v_add_f32_e32 v23, v53, v26
	v_mul_f32_e32 v22, 0x3fb8aa3b, v22
	v_mul_f32_e32 v23, 0xbfb8aa3b, v23
	v_exp_f32_e32 v22, v22
	v_add_f32_e32 v14, 1.0, v14
	v_exp_f32_e32 v23, v23
	v_rcp_f32_e32 v14, v14
	v_mul_f32_e32 v20, v24, v25
	v_add_f32_e32 v4, v54, v4
	s_waitcnt lgkmcnt(1)
	v_mul_f32_e32 v20, v20, v55
	v_add_u32_e32 v21, s0, v21
	v_mul_f32_e32 v4, 0xbfb8aa3b, v4
	ds_write_b32 v21, v20
	v_fma_f32 v21, -v22, v22, 1.0
	v_exp_f32_e32 v4, v4
	v_add_f32_e32 v20, 1.0, v23
	v_max_f32_e32 v21, 0, v21
	v_or_b32_e32 v13, 0x2200, v84
	v_mul_f32_e32 v14, 0xc1000000, v14
	v_rcp_f32_e32 v20, v20
	v_sqrt_f32_e32 v21, v21
	ds_read_b32 v23, v74 offset:8580
	v_add_u32_e32 v15, 0, v13
	v_mul_f32_e32 v14, v57, v14
	ds_write_b32 v15, v22 offset:62720
	v_add_f32_e32 v15, v53, v27
	v_mul_f32_e32 v14, 0x3fb8aa3b, v14
	v_mul_f32_e32 v15, 0xbfb8aa3b, v15
	v_exp_f32_e32 v14, v14
	v_add_f32_e32 v4, 1.0, v4
	v_exp_f32_e32 v15, v15
	v_rcp_f32_e32 v4, v4
	v_mul_f32_e32 v12, v20, v21
	s_waitcnt lgkmcnt(1)
	v_mul_f32_e32 v12, v12, v23
	v_add_u32_e32 v13, s0, v13
	v_mfma_f32_16x16x32_bf16 v[0:3], v[16:19], v[0:3], v[8:11]
	v_add_f32_e32 v5, v54, v5
	ds_write_b32 v13, v12
	v_fma_f32 v13, -v14, v14, 1.0
	v_mul_f32_e32 v5, 0xbfb8aa3b, v5
	v_add_f32_e32 v12, 1.0, v15
	v_max_f32_e32 v13, 0, v13
	v_mul_f32_e32 v4, 0xc1000000, v4
	v_exp_f32_e32 v5, v5
	v_rcp_f32_e32 v12, v12
	v_sqrt_f32_e32 v13, v13
	ds_read_b32 v15, v74 offset:8840
	v_mul_f32_e32 v4, v57, v4
	v_add_f32_e32 v0, v53, v0
	v_mul_f32_e32 v4, 0x3fb8aa3b, v4
	v_mul_f32_e32 v0, 0xbfb8aa3b, v0
	v_exp_f32_e32 v4, v4
	v_exp_f32_e32 v0, v0
	v_add_f32_e32 v5, 1.0, v5
	v_mul_f32_e32 v8, v12, v13
	v_or_b32_e32 v9, 0x2300, v84
	v_rcp_f32_e32 v5, v5
	s_waitcnt lgkmcnt(0)
	v_mul_f32_e32 v8, v8, v15
	v_add_u32_e32 v10, 0, v9
	v_add_u32_e32 v9, s0, v9
	ds_write_b32 v9, v8
	v_fma_f32 v8, -v4, v4, 1.0
	ds_write_b32 v10, v14 offset:62720
	v_add_f32_e32 v0, 1.0, v0
	v_max_f32_e32 v8, 0, v8
	v_rcp_f32_e32 v0, v0
	v_sqrt_f32_e32 v8, v8
	ds_read_b32 v9, v74 offset:12220
	v_mul_f32_e32 v5, 0xc1000000, v5
	v_add_f32_e32 v1, v53, v1
	v_mul_f32_e32 v5, v57, v5
	v_mul_f32_e32 v1, 0xbfb8aa3b, v1
	v_mul_f32_e32 v5, 0x3fb8aa3b, v5
	v_exp_f32_e32 v1, v1
	v_exp_f32_e32 v5, v5
	v_mul_f32_e32 v0, v0, v8
	v_or_b32_e32 v8, 0x3000, v84
	s_waitcnt lgkmcnt(0)
	v_mul_f32_e32 v0, v0, v9
	v_add_u32_e32 v9, 0, v8
	ds_write_b32 v9, v4 offset:62720
	v_add_u32_e32 v4, s0, v8
	ds_write_b32 v4, v0
	v_add_f32_e32 v0, 1.0, v1
	v_fma_f32 v1, -v5, v5, 1.0
	v_max_f32_e32 v1, 0, v1
	v_rcp_f32_e32 v0, v0
	v_sqrt_f32_e32 v1, v1
	ds_read_b32 v4, v74 offset:12480
	v_add_f32_e32 v2, v53, v2
	v_mul_f32_e32 v2, 0xbfb8aa3b, v2
	v_mul_f32_e32 v0, v0, v1
	v_exp_f32_e32 v2, v2
	s_waitcnt lgkmcnt(0)
	v_mul_f32_e32 v0, v0, v4
	v_add_f32_e32 v4, v54, v6
	v_mul_f32_e32 v4, 0xbfb8aa3b, v4
	v_exp_f32_e32 v4, v4
	v_or_b32_e32 v1, 0x3100, v84
	v_add_u32_e32 v6, 0, v1
	v_add_u32_e32 v1, s0, v1
	v_add_f32_e32 v4, 1.0, v4
	v_rcp_f32_e32 v4, v4
	ds_write_b32 v1, v0
	ds_write_b32 v6, v5 offset:62720
	v_add_f32_e32 v0, 1.0, v2
	v_mul_f32_e32 v4, 0xc1000000, v4
	v_mul_f32_e32 v4, v57, v4
	v_mul_f32_e32 v4, 0x3fb8aa3b, v4
	v_exp_f32_e32 v4, v4
	v_rcp_f32_e32 v0, v0
	ds_read_b32 v2, v74 offset:12740
	v_add_f32_e32 v3, v53, v3
	v_fma_f32 v1, -v4, v4, 1.0
	v_max_f32_e32 v1, 0, v1
	v_sqrt_f32_e32 v1, v1
	v_mul_f32_e32 v3, 0xbfb8aa3b, v3
	v_exp_f32_e32 v3, v3
	v_lshlrev_b32_e32 v20, 4, v33
	v_mul_f32_e32 v0, v0, v1
	s_waitcnt lgkmcnt(0)
	v_mul_f32_e32 v0, v0, v2
	v_add_f32_e32 v2, v54, v7
	v_mul_f32_e32 v2, 0xbfb8aa3b, v2
	v_exp_f32_e32 v2, v2
	v_or_b32_e32 v1, 0x3200, v84
	v_add_u32_e32 v5, 0, v1
	v_add_u32_e32 v1, s0, v1
	v_add_f32_e32 v2, 1.0, v2
	v_rcp_f32_e32 v2, v2
	ds_write_b32 v1, v0
	ds_write_b32 v5, v4 offset:62720
	v_add_f32_e32 v0, 1.0, v3
	v_mul_f32_e32 v2, 0xc1000000, v2
	v_mul_f32_e32 v2, v57, v2
	v_mul_f32_e32 v2, 0x3fb8aa3b, v2
	v_exp_f32_e32 v2, v2
	v_rcp_f32_e32 v0, v0
	ds_read_b32 v3, v74 offset:13000
	v_lshl_or_b32 v57, v48, 12, v29
	v_fma_f32 v1, -v2, v2, 1.0
	v_max_f32_e32 v1, 0, v1
	v_sqrt_f32_e32 v1, v1
	v_or_b32_e32 v8, 11, v20
	v_sub_u32_e32 v9, 63, v8
	v_cndmask_b32_e32 v8, v9, v8, vcc
	v_mul_f32_e32 v0, v0, v1
	v_or_b32_e32 v1, 0x3300, v84
	s_waitcnt lgkmcnt(0)
	v_mul_f32_e32 v0, v0, v3
	v_add_u32_e32 v3, 0, v1
	ds_write_b32 v3, v2 offset:62720
	v_or_b32_e32 v2, 1, v20
	v_sub_u32_e32 v3, 63, v2
	v_cndmask_b32_e32 v2, v3, v2, vcc
	v_lshlrev_b32_e32 v2, 6, v2
	v_add_lshl_u32 v2, v2, v57, 2
	v_add_u32_e32 v16, 0, v2
	v_add_u32_e32 v22, s0, v2
	v_or_b32_e32 v2, 2, v20
	v_sub_u32_e32 v3, 63, v2
	v_cndmask_b32_e32 v2, v3, v2, vcc
	v_lshlrev_b32_e32 v2, 6, v2
	v_add_u32_e32 v1, s0, v1
	v_add_lshl_u32 v2, v2, v57, 2
	ds_write_b32 v1, v0
	v_sub_u32_e32 v0, 63, v20
	v_add_u32_e32 v23, 0, v2
	v_add_u32_e32 v24, s0, v2
	v_or_b32_e32 v2, 3, v20
	v_cndmask_b32_e32 v0, v0, v20, vcc
	v_sub_u32_e32 v3, 63, v2
	v_lshlrev_b32_e32 v0, 6, v0
	v_cndmask_b32_e32 v2, v3, v2, vcc
	v_add_lshl_u32 v1, v0, v57, 2
	v_lshlrev_b32_e32 v2, 6, v2
	v_add_u32_e32 v0, 0, v1
	v_add_lshl_u32 v2, v2, v57, 2
	s_waitcnt lgkmcnt(0)
	s_barrier
	s_and_b32 s0, s44, 1
	s_lshr_b32 s1, s44, 1
	v_and_b32_e32 v190, 63, v195
	v_lshlrev_b32_e32 v189, 3, v195
	s_cmp_eq_u32 s0, 0
	s_cbranch_scc0 .Lrgs_p5_b1
	s_lshl_b32 s2, s1, 12
	s_add_i32 s2, s2, 0xf500
	v_lshl_add_u32 v188, v190, 2, s2
	ds_read_b32 v154, v188 offset:0
	ds_read_b32 v170, v188 offset:32768
	ds_read_b32 v155, v188 offset:256
	ds_read_b32 v171, v188 offset:33024
	ds_read_b32 v156, v188 offset:512
	ds_read_b32 v172, v188 offset:33280
	ds_read_b32 v157, v188 offset:768
	ds_read_b32 v173, v188 offset:33536
	ds_read_b32 v158, v188 offset:1024
	ds_read_b32 v174, v188 offset:33792
	ds_read_b32 v159, v188 offset:1280
	ds_read_b32 v175, v188 offset:34048
	ds_read_b32 v160, v188 offset:1536
	ds_read_b32 v176, v188 offset:34304
	s_waitcnt lgkmcnt(12)
	v_mov_b32_e32 v186, v170
	v_mov_b32_e32 v187, v154
	ds_read_b32 v161, v188 offset:1792
	ds_read_b32 v177, v188 offset:34560
	s_waitcnt lgkmcnt(12)
	v_fma_f32 v186, v155, v186, v171
	v_mul_f32_e32 v187, v187, v155
	ds_read_b32 v162, v188 offset:2048
	ds_read_b32 v178, v188 offset:34816
	s_waitcnt lgkmcnt(12)
	v_fma_f32 v186, v156, v186, v172
	v_mul_f32_e32 v187, v187, v156
	ds_read_b32 v163, v188 offset:2304
	ds_read_b32 v179, v188 offset:35072
	s_waitcnt lgkmcnt(12)
	v_fma_f32 v186, v157, v186, v173
	v_mul_f32_e32 v187, v187, v157
	ds_read_b32 v164, v188 offset:2560
	ds_read_b32 v180, v188 offset:35328
	s_waitcnt lgkmcnt(12)
	v_fma_f32 v186, v158, v186, v174
	v_mul_f32_e32 v187, v187, v158
	ds_read_b32 v165, v188 offset:2816
	ds_read_b32 v181, v188 offset:35584
	s_waitcnt lgkmcnt(12)
	v_fma_f32 v186, v159, v186, v175
	v_mul_f32_e32 v187, v187, v159
	ds_read_b32 v166, v188 offset:3072
	ds_read_b32 v182, v188 offset:35840
	s_waitcnt lgkmcnt(12)
	v_fma_f32 v186, v160, v186, v176
	v_mul_f32_e32 v187, v187, v160
	ds_read_b32 v167, v188 offset:3328
	ds_read_b32 v183, v188 offset:36096
	s_waitcnt lgkmcnt(12)
	v_fma_f32 v186, v161, v186, v177
	v_mul_f32_e32 v187, v187, v161
	ds_read_b32 v168, v188 offset:3584
	ds_read_b32 v184, v188 offset:36352
	s_waitcnt lgkmcnt(12)
	v_fma_f32 v186, v162, v186, v178
	v_mul_f32_e32 v187, v187, v162
	ds_read_b32 v169, v188 offset:3840
	ds_read_b32 v185, v188 offset:36608
	s_waitcnt lgkmcnt(12)
	v_fma_f32 v186, v163, v186, v179
	v_mul_f32_e32 v187, v187, v163
	s_waitcnt lgkmcnt(10)
	v_fma_f32 v186, v164, v186, v180
	v_mul_f32_e32 v187, v187, v164
	s_waitcnt lgkmcnt(8)
	v_fma_f32 v186, v165, v186, v181
	v_mul_f32_e32 v187, v187, v165
	s_waitcnt lgkmcnt(6)
	v_fma_f32 v186, v166, v186, v182
	v_mul_f32_e32 v187, v187, v166
	s_waitcnt lgkmcnt(4)
	v_fma_f32 v186, v167, v186, v183
	v_mul_f32_e32 v187, v187, v167
	s_waitcnt lgkmcnt(2)
	v_fma_f32 v186, v168, v186, v184
	v_mul_f32_e32 v187, v187, v168
	s_waitcnt lgkmcnt(0)
	v_fma_f32 v186, v169, v186, v185
	v_mul_f32_e32 v187, v187, v169
	v_mov_b32_e32 v190, v187
	v_mov_b32_e32 v191, v186
	ds_write_b64 v189, v[190:191]
	s_branch .Lrgs_p5_j1

.LBB0_810:
	s_mov_b32 s33, 1
	s_andn2_b64 vcc, exec, s[70:71]
	s_mov_b64 s[72:73], 0
	s_cbranch_vccnz .LBB0_738
	v_readlane_b32 s46, v254, 28
	v_readlane_b32 s44, v254, 9
	v_readlane_b32 s45, v254, 10
	v_lshlrev_b32_e32 v100, 2, v68
	s_lshl_b32 s46, s46, 2
	s_add_u32 s44, s44, s46
	s_addc_u32 s45, s45, 0
	s_nop 0
	global_load_dwordx4 v[126:129], v100, s[44:45] offset:1024
	global_load_dwordx4 v[130:133], v100, s[44:45] offset:1088
	global_load_dwordx4 v[134:137], v100, s[44:45] offset:1152
	global_load_dwordx4 v[138:141], v100, s[44:45] offset:1216
	global_load_dwordx4 v[142:145], v100, s[44:45] offset:1280
	global_load_dwordx4 v[146:149], v100, s[44:45] offset:1344
	global_load_dwordx4 v[150:153], v100, s[44:45] offset:1408
	global_load_dwordx4 v[154:157], v100, s[44:45] offset:1472
	v_pk_mul_f32 v[0:1], v[84:85], v[84:85]
	v_pk_mul_f32 v[2:3], v[82:83], v[82:83]
	v_add_f32_e32 v0, v0, v1
	v_add_f32_e32 v0, v2, v0
	v_pk_mul_f32 v[4:5], v[78:79], v[78:79]
	v_add_f32_e32 v0, v3, v0
	v_add_f32_e32 v0, v0, v4
	v_pk_mul_f32 v[6:7], v[76:77], v[76:77]
	v_add_f32_e32 v0, v5, v0
	v_add_f32_e32 v0, v6, v0
	v_pk_mul_f32 v[8:9], v[72:73], v[72:73]
	v_add_f32_e32 v0, v7, v0
	v_add_f32_e32 v0, v0, v8
	v_pk_mul_f32 v[10:11], v[70:71], v[70:71]
	v_add_f32_e32 v0, v9, v0
	v_add_f32_e32 v0, v10, v0
	v_pk_mul_f32 v[12:13], v[64:65], v[64:65]
	v_add_f32_e32 v0, v11, v0
	v_add_f32_e32 v0, v0, v12
	v_pk_mul_f32 v[14:15], v[62:63], v[62:63]
	v_add_f32_e32 v0, v13, v0
	v_add_f32_e32 v0, v14, v0
	s_waitcnt vmcnt(0)
	v_pk_mul_f32 v[16:17], v[58:59], v[58:59]
	v_add_f32_e32 v0, v15, v0
	v_add_f32_e32 v0, v0, v16
	v_pk_mul_f32 v[18:19], v[56:57], v[56:57]
	v_add_f32_e32 v0, v17, v0
	v_add_f32_e32 v0, v18, v0
	v_pk_mul_f32 v[20:21], v[52:53], v[52:53]
	v_add_f32_e32 v0, v19, v0
	v_add_f32_e32 v0, v0, v20
	v_pk_mul_f32 v[22:23], v[50:51], v[50:51]
	v_add_f32_e32 v0, v21, v0
	v_add_f32_e32 v0, v22, v0
	v_pk_mul_f32 v[24:25], v[46:47], v[46:47]
	v_add_f32_e32 v0, v23, v0
	v_add_f32_e32 v0, v0, v24
	v_pk_mul_f32 v[26:27], v[44:45], v[44:45]
	v_add_f32_e32 v0, v25, v0
	v_add_f32_e32 v0, v26, v0
	v_pk_mul_f32 v[28:29], v[42:43], v[42:43]
	v_add_f32_e32 v0, v27, v0
	v_add_f32_e32 v0, v0, v28
	v_pk_mul_f32 v[30:31], v[40:41], v[40:41]
	v_add_f32_e32 v0, v29, v0
	v_add_f32_e32 v0, v30, v0
	v_add_f32_e32 v0, v31, v0
	ds_bpermute_b32 v1, v69, v0
	s_mov_b32 s0, 0x800000
	v_readlane_b32 s96, v254, 28
	v_readlane_b32 s2, v254, 9
	v_readlane_b32 s3, v254, 10
	s_waitcnt lgkmcnt(0)
	v_add_f32_e32 v0, v0, v1
	ds_bpermute_b32 v1, v108, v0
	v_readlane_b32 s84, v253, 41
	v_readlane_b32 s97, v254, 29
	v_readlane_b32 s88, v253, 45
	v_readlane_b32 s89, v253, 46
	s_waitcnt lgkmcnt(0)
	v_add_f32_e32 v0, v0, v1
	v_fmamk_f32 v0, v0, 0x3c000000, v194
	v_cmp_gt_f32_e32 vcc, s0, v0
	v_mul_f32_e32 v1, 0x4b800000, v0
	s_lshl_b32 s0, s96, 2
	v_cndmask_b32_e32 v0, v0, v1, vcc
	v_rsq_f32_e32 v0, v0
	s_add_u32 s0, s2, s0
	s_addc_u32 s1, s3, 0
	v_readlane_b32 s2, v254, 30
	v_mul_f32_e32 v1, 0x45800000, v0
	v_cndmask_b32_e32 v4, v0, v1, vcc
	v_lshlrev_b64 v[0:1], 11, v[198:199]
	v_readlane_b32 s3, v254, 31
	v_lshl_add_u64 v[0:1], s[88:89], 0, v[0:1]
	s_mov_b32 s3, s97
	v_lshl_add_u64 v[6:7], v[0:1], 0, s[2:3]
	v_lshlrev_b32_e32 v0, 16, v88
	v_mul_f32_e32 v0, 0xbfb8aa3b, v0
	v_exp_f32_e32 v0, v0
	v_lshlrev_b32_e32 v5, 2, v68
	v_pk_mul_f32 v[10:11], v[84:85], v[4:5] op_sel_hi:[1,0]
	v_lshlrev_b32_e32 v192, 1, v68
	v_add_f32_e32 v0, 1.0, v0
	v_rcp_f32_e32 v8, v0
	v_and_b32_e32 v0, 0xffff0000, v88
	v_mul_f32_e32 v0, 0xbfb8aa3b, v0
	v_exp_f32_e32 v0, v0
	s_mov_b64 s[2:3], 0x8000200
	v_readlane_b32 s91, v253, 48
	v_readlane_b32 s82, v253, 49
	v_add_f32_e32 v0, 1.0, v0
	v_rcp_f32_e32 v9, v0
	v_mov_b64_e32 v[0:1], v[126:127]
	v_mov_b64_e32 v[2:3], v[128:129]
	v_readlane_b32 s85, v253, 42
	v_readlane_b32 s86, v253, 43
	v_readlane_b32 s87, v253, 44
	v_readlane_b32 s90, v253, 47
	v_readlane_b32 s83, v253, 50
	s_movk_i32 s91, 0x80
	s_movk_i32 s92, 0x1a00
	s_movk_i32 s93, 0x110
	v_readlane_b32 s94, v253, 52
	v_readlane_b32 s29, v254, 24
	v_readlane_b32 s30, v254, 18
	v_readlane_b32 s14, v254, 19
	v_readlane_b32 s13, v254, 25
	v_readlane_b32 s15, v254, 20
	v_pk_mul_f32 v[0:1], v[0:1], v[10:11]
	s_nop 0
	v_pk_mul_f32 v[0:1], v[8:9], v[0:1]
	v_lshlrev_b32_e32 v8, 16, v89
	v_and_b32_e32 v9, 0xffff0000, v89
	v_mul_f32_e32 v8, 0xbfb8aa3b, v8
	v_mul_f32_e32 v9, 0xbfb8aa3b, v9
	v_exp_f32_e32 v8, v8
	v_exp_f32_e32 v9, v9
	v_pk_mul_f32 v[10:11], v[82:83], v[4:5] op_sel_hi:[1,0]
	v_add_f32_e32 v8, 1.0, v8
	v_add_f32_e32 v9, 1.0, v9
	v_rcp_f32_e32 v8, v8
	v_rcp_f32_e32 v9, v9
	v_pk_mul_f32 v[2:3], v[2:3], v[10:11]
	v_pk_mul_f32 v[10:11], v[78:79], v[4:5] op_sel_hi:[1,0]
	v_pk_mul_f32 v[2:3], v[8:9], v[2:3]
	s_nop 0
	v_cvt_pk_bf16_f32 v9, v2, v3
	v_lshl_add_u64 v[2:3], v[6:7], 0, v[192:193]
	v_cvt_pk_bf16_f32 v8, v0, v1
	v_lshl_add_u64 v[0:1], v[2:3], 0, s[2:3]
	s_brev_b32 s2, 16
	v_add_co_u32_e32 v2, vcc, s2, v2
	s_nop 1
	v_addc_co_u32_e32 v3, vcc, 0, v3, vcc
	global_store_dwordx2 v[2:3], v[8:9], off offset:512
	v_mov_b64_e32 v[6:7], v[130:131]
	v_mov_b64_e32 v[8:9], v[132:133]
	v_lshlrev_b32_e32 v2, 16, v86
	v_and_b32_e32 v3, 0xffff0000, v86
	v_mul_f32_e32 v2, 0xbfb8aa3b, v2
	v_mul_f32_e32 v3, 0xbfb8aa3b, v3
	v_exp_f32_e32 v2, v2
	v_exp_f32_e32 v3, v3
	v_add_f32_e32 v2, 1.0, v2
	v_add_f32_e32 v3, 1.0, v3
	v_rcp_f32_e32 v2, v2
	v_rcp_f32_e32 v3, v3
	v_pk_mul_f32 v[6:7], v[6:7], v[10:11]
	s_nop 0
	v_pk_mul_f32 v[2:3], v[2:3], v[6:7]
	v_lshlrev_b32_e32 v6, 16, v87
	v_and_b32_e32 v7, 0xffff0000, v87
	v_mul_f32_e32 v6, 0xbfb8aa3b, v6
	v_mul_f32_e32 v7, 0xbfb8aa3b, v7
	v_exp_f32_e32 v6, v6
	v_exp_f32_e32 v7, v7
	v_pk_mul_f32 v[10:11], v[76:77], v[4:5] op_sel_hi:[1,0]
	v_cvt_pk_bf16_f32 v2, v2, v3
	v_add_f32_e32 v6, 1.0, v6
	v_add_f32_e32 v7, 1.0, v7
	v_rcp_f32_e32 v6, v6
	v_rcp_f32_e32 v7, v7
	v_pk_mul_f32 v[8:9], v[8:9], v[10:11]
	v_pk_mul_f32 v[10:11], v[72:73], v[4:5] op_sel_hi:[1,0]
	v_pk_mul_f32 v[6:7], v[6:7], v[8:9]
	s_nop 0
	v_cvt_pk_bf16_f32 v3, v6, v7
	global_store_dwordx2 v[0:1], v[2:3], off offset:32
	v_mov_b64_e32 v[6:7], v[134:135]
	v_mov_b64_e32 v[8:9], v[136:137]
	v_lshlrev_b32_e32 v2, 16, v80
	v_and_b32_e32 v3, 0xffff0000, v80
	v_mul_f32_e32 v2, 0xbfb8aa3b, v2
	v_mul_f32_e32 v3, 0xbfb8aa3b, v3
	v_exp_f32_e32 v2, v2
	v_exp_f32_e32 v3, v3
	v_add_f32_e32 v2, 1.0, v2
	v_add_f32_e32 v3, 1.0, v3
	v_rcp_f32_e32 v2, v2
	v_rcp_f32_e32 v3, v3
	v_pk_mul_f32 v[6:7], v[10:11], v[6:7]
	s_nop 0
	v_pk_mul_f32 v[2:3], v[2:3], v[6:7]
	v_lshlrev_b32_e32 v6, 16, v81
	v_and_b32_e32 v7, 0xffff0000, v81
	v_mul_f32_e32 v6, 0xbfb8aa3b, v6
	v_mul_f32_e32 v7, 0xbfb8aa3b, v7
	v_exp_f32_e32 v6, v6
	v_exp_f32_e32 v7, v7
	v_pk_mul_f32 v[10:11], v[70:71], v[4:5] op_sel_hi:[1,0]
	v_cvt_pk_bf16_f32 v2, v2, v3
	v_add_f32_e32 v6, 1.0, v6
	v_add_f32_e32 v7, 1.0, v7
	v_rcp_f32_e32 v6, v6
	v_rcp_f32_e32 v7, v7
	v_pk_mul_f32 v[8:9], v[10:11], v[8:9]
	v_pk_mul_f32 v[10:11], v[64:65], v[4:5] op_sel_hi:[1,0]
	v_pk_mul_f32 v[6:7], v[6:7], v[8:9]
	s_nop 0
	v_cvt_pk_bf16_f32 v3, v6, v7
	global_store_dwordx2 v[0:1], v[2:3], off offset:64
	v_mov_b64_e32 v[6:7], v[138:139]
	v_mov_b64_e32 v[8:9], v[140:141]
	v_lshlrev_b32_e32 v2, 16, v74
	v_and_b32_e32 v3, 0xffff0000, v74
	v_mul_f32_e32 v2, 0xbfb8aa3b, v2
	v_mul_f32_e32 v3, 0xbfb8aa3b, v3
	v_exp_f32_e32 v2, v2
	v_exp_f32_e32 v3, v3
	v_add_f32_e32 v2, 1.0, v2
	v_add_f32_e32 v3, 1.0, v3
	v_rcp_f32_e32 v2, v2
	v_rcp_f32_e32 v3, v3
	v_pk_mul_f32 v[6:7], v[10:11], v[6:7]
	s_nop 0
	v_pk_mul_f32 v[2:3], v[2:3], v[6:7]
	v_lshlrev_b32_e32 v6, 16, v75
	v_and_b32_e32 v7, 0xffff0000, v75
	v_mul_f32_e32 v6, 0xbfb8aa3b, v6
	v_mul_f32_e32 v7, 0xbfb8aa3b, v7
	v_exp_f32_e32 v6, v6
	v_exp_f32_e32 v7, v7
	v_pk_mul_f32 v[10:11], v[62:63], v[4:5] op_sel_hi:[1,0]
	v_cvt_pk_bf16_f32 v2, v2, v3
	v_add_f32_e32 v6, 1.0, v6
	v_add_f32_e32 v7, 1.0, v7
	v_rcp_f32_e32 v6, v6
	v_rcp_f32_e32 v7, v7
	v_pk_mul_f32 v[8:9], v[10:11], v[8:9]
	v_pk_mul_f32 v[10:11], v[58:59], v[4:5] op_sel_hi:[1,0]
	v_pk_mul_f32 v[6:7], v[6:7], v[8:9]
	s_nop 0
	v_cvt_pk_bf16_f32 v3, v6, v7
	global_store_dwordx2 v[0:1], v[2:3], off offset:96
	v_mov_b64_e32 v[6:7], v[142:143]
	v_mov_b64_e32 v[8:9], v[144:145]
	v_lshlrev_b32_e32 v2, 16, v66
	v_and_b32_e32 v3, 0xffff0000, v66
	v_mul_f32_e32 v2, 0xbfb8aa3b, v2
	v_mul_f32_e32 v3, 0xbfb8aa3b, v3
	v_exp_f32_e32 v2, v2
	v_exp_f32_e32 v3, v3
	v_add_f32_e32 v2, 1.0, v2
	v_add_f32_e32 v3, 1.0, v3
	v_rcp_f32_e32 v2, v2
	v_rcp_f32_e32 v3, v3
	v_pk_mul_f32 v[6:7], v[10:11], v[6:7]
	s_nop 0
	v_pk_mul_f32 v[2:3], v[2:3], v[6:7]
	v_lshlrev_b32_e32 v6, 16, v67
	v_and_b32_e32 v7, 0xffff0000, v67
	v_mul_f32_e32 v6, 0xbfb8aa3b, v6
	v_mul_f32_e32 v7, 0xbfb8aa3b, v7
	v_exp_f32_e32 v6, v6
	v_exp_f32_e32 v7, v7
	v_pk_mul_f32 v[10:11], v[56:57], v[4:5] op_sel_hi:[1,0]
	v_cvt_pk_bf16_f32 v2, v2, v3
	v_add_f32_e32 v6, 1.0, v6
	v_add_f32_e32 v7, 1.0, v7
	v_rcp_f32_e32 v6, v6
	v_rcp_f32_e32 v7, v7
	v_pk_mul_f32 v[8:9], v[10:11], v[8:9]
	v_pk_mul_f32 v[10:11], v[52:53], v[4:5] op_sel_hi:[1,0]
	v_pk_mul_f32 v[6:7], v[6:7], v[8:9]
	s_nop 0
	v_cvt_pk_bf16_f32 v3, v6, v7
	global_store_dwordx2 v[0:1], v[2:3], off offset:128
	v_mov_b64_e32 v[6:7], v[146:147]
	v_mov_b64_e32 v[8:9], v[148:149]
	v_lshlrev_b32_e32 v2, 16, v60
	v_and_b32_e32 v3, 0xffff0000, v60
	v_mul_f32_e32 v2, 0xbfb8aa3b, v2
	v_mul_f32_e32 v3, 0xbfb8aa3b, v3
	v_exp_f32_e32 v2, v2
	v_exp_f32_e32 v3, v3
	v_add_f32_e32 v2, 1.0, v2
	v_add_f32_e32 v3, 1.0, v3
	v_rcp_f32_e32 v2, v2
	v_rcp_f32_e32 v3, v3
	v_pk_mul_f32 v[6:7], v[10:11], v[6:7]
	s_nop 0
	v_pk_mul_f32 v[2:3], v[2:3], v[6:7]
	v_lshlrev_b32_e32 v6, 16, v61
	v_and_b32_e32 v7, 0xffff0000, v61
	v_mul_f32_e32 v6, 0xbfb8aa3b, v6
	v_mul_f32_e32 v7, 0xbfb8aa3b, v7
	v_exp_f32_e32 v6, v6
	v_exp_f32_e32 v7, v7
	v_pk_mul_f32 v[10:11], v[50:51], v[4:5] op_sel_hi:[1,0]
	v_cvt_pk_bf16_f32 v2, v2, v3
	v_add_f32_e32 v6, 1.0, v6
	v_add_f32_e32 v7, 1.0, v7
	v_rcp_f32_e32 v6, v6
	v_rcp_f32_e32 v7, v7
	v_pk_mul_f32 v[8:9], v[10:11], v[8:9]
	v_pk_mul_f32 v[10:11], v[46:47], v[4:5] op_sel_hi:[1,0]
	v_pk_mul_f32 v[6:7], v[6:7], v[8:9]
	s_nop 0
	v_cvt_pk_bf16_f32 v3, v6, v7
	global_store_dwordx2 v[0:1], v[2:3], off offset:160
	v_mov_b64_e32 v[6:7], v[150:151]
	v_mov_b64_e32 v[8:9], v[152:153]
	v_lshlrev_b32_e32 v2, 16, v54
	v_and_b32_e32 v3, 0xffff0000, v54
	v_mul_f32_e32 v2, 0xbfb8aa3b, v2
	v_mul_f32_e32 v3, 0xbfb8aa3b, v3
	v_exp_f32_e32 v2, v2
	v_exp_f32_e32 v3, v3
	v_add_f32_e32 v2, 1.0, v2
	v_add_f32_e32 v3, 1.0, v3
	v_rcp_f32_e32 v2, v2
	v_rcp_f32_e32 v3, v3
	v_pk_mul_f32 v[6:7], v[10:11], v[6:7]
	s_nop 0
	v_pk_mul_f32 v[2:3], v[2:3], v[6:7]
	v_lshlrev_b32_e32 v6, 16, v55
	v_and_b32_e32 v7, 0xffff0000, v55
	v_mul_f32_e32 v6, 0xbfb8aa3b, v6
	v_mul_f32_e32 v7, 0xbfb8aa3b, v7
	v_exp_f32_e32 v6, v6
	v_exp_f32_e32 v7, v7
	v_pk_mul_f32 v[10:11], v[44:45], v[4:5] op_sel_hi:[1,0]
	v_cvt_pk_bf16_f32 v2, v2, v3
	v_add_f32_e32 v6, 1.0, v6
	v_add_f32_e32 v7, 1.0, v7
	v_rcp_f32_e32 v6, v6
	v_rcp_f32_e32 v7, v7
	v_pk_mul_f32 v[8:9], v[10:11], v[8:9]
	v_pk_mul_f32 v[10:11], v[42:43], v[4:5] op_sel_hi:[1,0]
	v_pk_mul_f32 v[6:7], v[6:7], v[8:9]
	s_nop 0
	v_cvt_pk_bf16_f32 v3, v6, v7
	global_store_dwordx2 v[0:1], v[2:3], off offset:192
	v_mov_b64_e32 v[6:7], v[154:155]
	v_mov_b64_e32 v[8:9], v[156:157]
	v_lshlrev_b32_e32 v2, 16, v48
	v_and_b32_e32 v3, 0xffff0000, v48
	v_mul_f32_e32 v2, 0xbfb8aa3b, v2
	v_mul_f32_e32 v3, 0xbfb8aa3b, v3
	v_exp_f32_e32 v2, v2
	v_exp_f32_e32 v3, v3
	v_lshlrev_b32_e32 v5, 16, v49
	v_mul_f32_e32 v5, 0xbfb8aa3b, v5
	v_add_f32_e32 v2, 1.0, v2
	v_add_f32_e32 v3, 1.0, v3
	v_exp_f32_e32 v5, v5
	v_rcp_f32_e32 v2, v2
	v_rcp_f32_e32 v3, v3
	v_add_f32_e32 v5, 1.0, v5
	v_pk_mul_f32 v[6:7], v[10:11], v[6:7]
	s_nop 0
	v_pk_mul_f32 v[2:3], v[2:3], v[6:7]
	v_rcp_f32_e32 v6, v5
	v_and_b32_e32 v5, 0xffff0000, v49
	v_mul_f32_e32 v5, 0xbfb8aa3b, v5
	v_exp_f32_e32 v5, v5
	v_cvt_pk_bf16_f32 v2, v2, v3
	v_add_f32_e32 v5, 1.0, v5
	v_rcp_f32_e32 v7, v5
	v_pk_mul_f32 v[4:5], v[40:41], v[4:5] op_sel_hi:[1,0]
	s_nop 0
	v_pk_mul_f32 v[4:5], v[4:5], v[8:9]
	s_nop 0
	v_pk_mul_f32 v[4:5], v[6:7], v[4:5]
	s_nop 0
	v_cvt_pk_bf16_f32 v3, v4, v5
	global_store_dwordx2 v[0:1], v[2:3], off offset:224
	s_branch .LBB0_638
